# v25 with wait-state fixes: s_nop between s_mov m0 and LDS-DMA at 4 sites left by the staging rebalance, and one s_nop restoring the 8-state MFMA-to-VALU distance in the scan loop
# baseline (speedup 1.0000x reference)
; #define PG8_STAGE(bufoff, gbase, voff) do { _Pragma("unroll") for (int _i = 0; _i < 2; ++_i) \
;         __builtin_amdgcn_global_load_lds((const unsigned*)((const char*)(gbase) + (voff)[_i]), (PG8_LAS unsigned*)(lds + (bufoff) + ldsw + _i * 8192), 16, 0, 0); } while (0)
; #define PG8_LDA(dst, b, h) do { _Pragma("unroll") for (int m = 0; m < 4; ++m) _Pragma("unroll") for (int k = 0; k < 2; ++k) dst[m][k] = *(const PG8_LAS bf16x8*)(lds + PG8_SA(b, h) + aoff + m * 2048 + k * 1024); } while (0)
; #define PG8_LDB(dst, b, h) do { _Pragma("unroll") for (int n = 0; n < 2; ++n) _Pragma("unroll") for (int k = 0; k < 2; ++k) dst[n][k] = *(const PG8_LAS bf16x8*)(lds + PG8_SB(b, h) + boff + n * 2048 + k * 1024); } while (0)
; #define PG8_MMA(ai, bj, At, Bt) do { __builtin_amdgcn_s_setprio(1); _Pragma("unroll") for (int m = 0; m < 4; ++m) _Pragma("unroll") for (int n = 0; n < 2; ++n) _Pragma("unroll") for (int k = 0; k < 2; ++k) \
;         acc[ai][bj][m][n] = __builtin_amdgcn_mfma_f32_16x16x32_bf16(Bt[n][k], At[m][k], acc[ai][bj][m][n], 0, 0, 0); __builtin_amdgcn_s_setprio(0); } while (0)
; #define PG8_WAIT_V(n) asm volatile("s_waitcnt vmcnt(" #n ")" ::: "memory")
; #define PG8_WAIT_L(n) asm volatile("s_waitcnt lgkmcnt(" #n ")" ::: "memory")
; #define PG8_BAR __builtin_amdgcn_s_barrier()
; #define PG8_SCHED __builtin_amdgcn_sched_barrier(0)
; template <class Epi, class Sched, bool ALIGN_EPI = false, bool SP2 = false>
; __device__ __forceinline__ void gemm_phase(PG8_LAS unsigned char* lds, const Gemm g, const Sched& S, const Epi& E) {
;     ...
;             PG8_LDB(B0, 0, 0); PG8_LDB(B1, 0, 1); PG8_SCHED; PG8_LDA(At, 0, 0); PG8_STAGE(PG8_SA(1, 1), a1 + hstep, voffA);
;             PG8_WAIT_V(8); PG8_WAIT_L(0); PG8_BAR; PG8_MMA(0, 0, At, B0); PG8_MMA(0, 1, At, B1); PG8_BAR; PG8_SCHED;
;             PG8_LDA(At, 0, 1); PG8_STAGE(PG8_SB(0, 0), b2, voffB); PG8_STAGE(PG8_SB(0, 1), b2 + hstep, voffB); PG8_STAGE(PG8_SA(0, 0), a2, voffA);
;             PG8_WAIT_V(8); PG8_WAIT_L(0); PG8_BAR; PG8_MMA(1, 0, At, B0); PG8_MMA(1, 1, At, B1); PG8_BAR; PG8_SCHED;
.LBB0_149:
	s_add_u32 s26, s22, 0xfff80080
	s_addc_u32 s27, s23, -1
	s_add_i32 s61, 0, 0x10000
	s_cmp_eq_u32 s56, 28
	s_cselect_b32 s37, s1, s27
	s_cselect_b32 s36, s9, s26
	v_add_u32_e32 v138, s61, v151
	s_cselect_b32 s27, s15, s31
	s_cselect_b32 s26, s17, s30
	s_add_i32 s76, 0, 0x14000
	ds_read_b128 v[154:157], v138
	ds_read_b128 v[160:163], v138 offset:1024
	ds_read_b128 v[164:167], v138 offset:2048
	ds_read_b128 v[168:171], v138 offset:3072
	v_add_u32_e32 v138, s76, v151
	ds_read_b128 v[172:175], v138
	ds_read_b128 v[176:179], v138 offset:1024
	ds_read_b128 v[180:183], v138 offset:2048
	ds_read_b128 v[184:187], v138 offset:3072
	v_lshl_add_u64 v[138:139], s[22:23], 0, v[134:135]
	s_add_i32 m0, s62, 0xc000
	ds_read_b128 v[188:191], v158
	ds_read_b128 v[192:195], v158 offset:1024
	ds_read_b128 v[196:199], v158 offset:2048
	ds_read_b128 v[208:211], v158 offset:3072
	ds_read_b128 v[212:215], v158 offset:4096
	ds_read_b128 v[216:219], v158 offset:5120
	ds_read_b128 v[220:223], v158 offset:6144
	ds_read_b128 v[224:227], v158 offset:7168
	global_load_lds_dwordx4 v[138:139], off
	v_lshl_add_u64 v[138:139], s[22:23], 0, v[136:137]
	s_add_i32 m0, s62, 0xe000
	s_nop 0
	global_load_lds_dwordx4 v[138:139], off
	v_lshl_add_u64 v[138:139], v[148:149], 0, s[84:85]
	s_mov_b32 m0, s67
	s_nop 0
	global_load_lds_dwordx4 v[138:139], off
	v_lshl_add_u64 v[138:139], v[228:229], 0, s[84:85]
	s_mov_b32 m0, s70
	s_nop 0
	global_load_lds_dwordx4 v[138:139], off
	s_waitcnt vmcnt(8)
	s_waitcnt lgkmcnt(0)
	s_barrier
	s_setprio 1
	s_waitcnt lgkmcnt(0)
	v_mfma_f32_16x16x32_bf16 v[124:127], v[154:157], v[188:191], v[124:127]
	v_mfma_f32_16x16x32_bf16 v[120:123], v[164:167], v[188:191], v[120:123]
	v_mfma_f32_16x16x32_bf16 v[108:111], v[154:157], v[196:199], v[108:111]
	v_mfma_f32_16x16x32_bf16 v[104:107], v[164:167], v[196:199], v[104:107]
	v_mfma_f32_16x16x32_bf16 v[92:95], v[154:157], v[212:215], v[92:95]
	v_mfma_f32_16x16x32_bf16 v[88:91], v[164:167], v[212:215], v[88:91]
	v_mfma_f32_16x16x32_bf16 v[76:79], v[154:157], v[220:223], v[76:79]
	v_mfma_f32_16x16x32_bf16 v[72:75], v[164:167], v[220:223], v[72:75]
	v_mfma_f32_16x16x32_bf16 v[124:127], v[160:163], v[192:195], v[124:127]
	v_mfma_f32_16x16x32_bf16 v[120:123], v[168:171], v[192:195], v[120:123]
	v_mfma_f32_16x16x32_bf16 v[108:111], v[160:163], v[208:211], v[108:111]
	v_mfma_f32_16x16x32_bf16 v[104:107], v[168:171], v[208:211], v[104:107]
	v_mfma_f32_16x16x32_bf16 v[92:95], v[160:163], v[216:219], v[92:95]
	v_mfma_f32_16x16x32_bf16 v[88:91], v[168:171], v[216:219], v[88:91]
	v_mfma_f32_16x16x32_bf16 v[76:79], v[160:163], v[224:227], v[76:79]
	v_mfma_f32_16x16x32_bf16 v[72:75], v[168:171], v[224:227], v[72:75]
	s_setprio 0
	s_setprio 1
	v_mfma_f32_16x16x32_bf16 v[116:119], v[172:175], v[188:191], v[116:119]
	v_mfma_f32_16x16x32_bf16 v[112:115], v[180:183], v[188:191], v[112:115]
	v_mfma_f32_16x16x32_bf16 v[100:103], v[172:175], v[196:199], v[100:103]
	v_mfma_f32_16x16x32_bf16 v[96:99], v[180:183], v[196:199], v[96:99]
	v_mfma_f32_16x16x32_bf16 v[84:87], v[172:175], v[212:215], v[84:87]
	v_mfma_f32_16x16x32_bf16 v[80:83], v[180:183], v[212:215], v[80:83]
	v_mfma_f32_16x16x32_bf16 v[68:71], v[172:175], v[220:223], v[68:71]
	v_mfma_f32_16x16x32_bf16 v[64:67], v[180:183], v[220:223], v[64:67]
	v_mfma_f32_16x16x32_bf16 v[116:119], v[176:179], v[192:195], v[116:119]
	v_mfma_f32_16x16x32_bf16 v[112:115], v[184:187], v[192:195], v[112:115]
	v_mfma_f32_16x16x32_bf16 v[100:103], v[176:179], v[208:211], v[100:103]
	v_mfma_f32_16x16x32_bf16 v[96:99], v[184:187], v[208:211], v[96:99]
	v_mfma_f32_16x16x32_bf16 v[84:87], v[176:179], v[216:219], v[84:87]
	v_mfma_f32_16x16x32_bf16 v[80:83], v[184:187], v[216:219], v[80:83]
	v_mfma_f32_16x16x32_bf16 v[68:71], v[176:179], v[224:227], v[68:71]
	v_mfma_f32_16x16x32_bf16 v[64:67], v[184:187], v[224:227], v[64:67]
	s_setprio 0
	s_barrier
	s_add_i32 s61, s61, s57
	v_lshl_add_u64 v[138:139], s[26:27], 0, v[140:141]
	s_mov_b32 m0, s61
	ds_read_b128 v[188:191], v158 offset:16384
	ds_read_b128 v[192:195], v158 offset:17408
	ds_read_b128 v[196:199], v158 offset:18432
	ds_read_b128 v[208:211], v158 offset:19456
	ds_read_b128 v[212:215], v158 offset:20480
	ds_read_b128 v[216:219], v158 offset:21504
	ds_read_b128 v[220:223], v158 offset:22528
	ds_read_b128 v[224:227], v158 offset:23552
	global_load_lds_dwordx4 v[138:139], off
	s_add_i32 m0, s61, 0x2000
	s_add_u32 s72, s26, 0x80000
	v_lshl_add_u64 v[146:147], s[26:27], 0, v[132:133]
	s_addc_u32 s73, s27, 0
	s_add_i32 s61, s76, s57
	global_load_lds_dwordx4 v[146:147], off
	v_lshl_add_u64 v[148:149], s[72:73], 0, v[140:141]
	s_mov_b32 m0, s61
	s_nop 0
	global_load_lds_dwordx4 v[148:149], off
	v_lshl_add_u64 v[148:149], s[72:73], 0, v[132:133]
	s_add_i32 m0, s61, 0x2000
	s_nop 0
	global_load_lds_dwordx4 v[148:149], off
	s_waitcnt vmcnt(4)
	s_waitcnt lgkmcnt(0)
	s_barrier
; #define PG8_STAGE(bufoff, gbase, voff) do { _Pragma("unroll") for (int _i = 0; _i < 2; ++_i) \
;         __builtin_amdgcn_global_load_lds((const unsigned*)((const char*)(gbase) + (voff)[_i]), (PG8_LAS unsigned*)(lds + (bufoff) + ldsw + _i * 8192), 16, 0, 0); } while (0)
; #define PG8_LDA(dst, b, h) do { _Pragma("unroll") for (int m = 0; m < 4; ++m) _Pragma("unroll") for (int k = 0; k < 2; ++k) dst[m][k] = *(const PG8_LAS bf16x8*)(lds + PG8_SA(b, h) + aoff + m * 2048 + k * 1024); } while (0)
; #define PG8_LDB(dst, b, h) do { _Pragma("unroll") for (int n = 0; n < 2; ++n) _Pragma("unroll") for (int k = 0; k < 2; ++k) dst[n][k] = *(const PG8_LAS bf16x8*)(lds + PG8_SB(b, h) + boff + n * 2048 + k * 1024); } while (0)
; #define PG8_MMA(ai, bj, At, Bt) do { __builtin_amdgcn_s_setprio(1); _Pragma("unroll") for (int m = 0; m < 4; ++m) _Pragma("unroll") for (int n = 0; n < 2; ++n) _Pragma("unroll") for (int k = 0; k < 2; ++k) \
;         acc[ai][bj][m][n] = __builtin_amdgcn_mfma_f32_16x16x32_bf16(Bt[n][k], At[m][k], acc[ai][bj][m][n], 0, 0, 0); __builtin_amdgcn_s_setprio(0); } while (0)
; #define PG8_WAIT_V(n) asm volatile("s_waitcnt vmcnt(" #n ")" ::: "memory")
; #define PG8_WAIT_L(n) asm volatile("s_waitcnt lgkmcnt(" #n ")" ::: "memory")
; #define PG8_BAR __builtin_amdgcn_s_barrier()
; #define PG8_SCHED __builtin_amdgcn_sched_barrier(0)
; template <class Epi, class Sched, bool ALIGN_EPI = false, bool SP2 = false>
; __device__ __forceinline__ void gemm_phase(PG8_LAS unsigned char* lds, const Gemm g, const Sched& S, const Epi& E) {
;     ...
;             PG8_WAIT_V(8); PG8_WAIT_L(0); PG8_BAR; PG8_MMA(1, 0, At, B0); PG8_MMA(1, 1, At, B1); PG8_BAR; PG8_SCHED;
;             PG8_LDB(B0, 1, 0); PG8_LDB(B1, 1, 1); PG8_SCHED; PG8_LDA(At, 1, 0); PG8_STAGE(PG8_SA(0, 1), a2 + hstep, voffA);
;             PG8_WAIT_V(8); PG8_WAIT_L(0); PG8_BAR; PG8_MMA(0, 0, At, B0); PG8_MMA(0, 1, At, B1); PG8_BAR; PG8_SCHED;
	s_setprio 1
	s_waitcnt lgkmcnt(0)
	v_mfma_f32_16x16x32_bf16 v[60:63], v[154:157], v[188:191], v[60:63]
	v_mfma_f32_16x16x32_bf16 v[56:59], v[164:167], v[188:191], v[56:59]
	v_mfma_f32_16x16x32_bf16 v[44:47], v[154:157], v[196:199], v[44:47]
	v_mfma_f32_16x16x32_bf16 v[40:43], v[164:167], v[196:199], v[40:43]
	v_mfma_f32_16x16x32_bf16 v[28:31], v[154:157], v[212:215], v[28:31]
	v_mfma_f32_16x16x32_bf16 v[24:27], v[164:167], v[212:215], v[24:27]
	v_mfma_f32_16x16x32_bf16 v[12:15], v[154:157], v[220:223], v[12:15]
	v_mfma_f32_16x16x32_bf16 v[8:11], v[164:167], v[220:223], v[8:11]
	v_mfma_f32_16x16x32_bf16 v[60:63], v[160:163], v[192:195], v[60:63]
	v_mfma_f32_16x16x32_bf16 v[56:59], v[168:171], v[192:195], v[56:59]
	v_mfma_f32_16x16x32_bf16 v[44:47], v[160:163], v[208:211], v[44:47]
	v_mfma_f32_16x16x32_bf16 v[40:43], v[168:171], v[208:211], v[40:43]
	v_mfma_f32_16x16x32_bf16 v[28:31], v[160:163], v[216:219], v[28:31]
	v_mfma_f32_16x16x32_bf16 v[24:27], v[168:171], v[216:219], v[24:27]
	v_mfma_f32_16x16x32_bf16 v[12:15], v[160:163], v[224:227], v[12:15]
	v_mfma_f32_16x16x32_bf16 v[8:11], v[168:171], v[224:227], v[8:11]
	s_setprio 0
	s_setprio 1
	v_mfma_f32_16x16x32_bf16 v[52:55], v[172:175], v[188:191], v[52:55]
	v_mfma_f32_16x16x32_bf16 v[48:51], v[180:183], v[188:191], v[48:51]
	v_mfma_f32_16x16x32_bf16 v[36:39], v[172:175], v[196:199], v[36:39]
	v_mfma_f32_16x16x32_bf16 v[32:35], v[180:183], v[196:199], v[32:35]
	v_mfma_f32_16x16x32_bf16 v[20:23], v[172:175], v[212:215], v[20:23]
	v_mfma_f32_16x16x32_bf16 v[16:19], v[180:183], v[212:215], v[16:19]
	v_mfma_f32_16x16x32_bf16 v[4:7], v[172:175], v[220:223], v[4:7]
	v_mfma_f32_16x16x32_bf16 v[0:3], v[180:183], v[220:223], v[0:3]
	v_mfma_f32_16x16x32_bf16 v[52:55], v[176:179], v[192:195], v[52:55]
	v_mfma_f32_16x16x32_bf16 v[48:51], v[184:187], v[192:195], v[48:51]
	v_mfma_f32_16x16x32_bf16 v[36:39], v[176:179], v[208:211], v[36:39]
	v_mfma_f32_16x16x32_bf16 v[32:35], v[184:187], v[208:211], v[32:35]
	v_mfma_f32_16x16x32_bf16 v[20:23], v[176:179], v[216:219], v[20:23]
	v_mfma_f32_16x16x32_bf16 v[16:19], v[184:187], v[216:219], v[16:19]
	v_mfma_f32_16x16x32_bf16 v[4:7], v[176:179], v[224:227], v[4:7]
	v_mfma_f32_16x16x32_bf16 v[0:3], v[184:187], v[224:227], v[0:3]
	s_setprio 0
	s_barrier
	s_add_i32 s61, 0, 0x18000
	v_add_u32_e32 v159, s61, v151
	s_add_i32 s72, 0, 0x1c000
	ds_read_b128 v[154:157], v159
	ds_read_b128 v[160:163], v159 offset:1024
	ds_read_b128 v[164:167], v159 offset:2048
	ds_read_b128 v[168:171], v159 offset:3072
	v_add_u32_e32 v159, s72, v151
	ds_read_b128 v[172:175], v159
	ds_read_b128 v[176:179], v159 offset:1024
	ds_read_b128 v[180:183], v159 offset:2048
	ds_read_b128 v[184:187], v159 offset:3072
	v_lshl_add_u64 v[148:149], s[36:37], 0, v[128:129]
	s_mov_b32 m0, s62
	s_nop 0
	global_load_lds_dwordx4 v[148:149], off
	v_lshl_add_u64 v[228:229], s[36:37], 0, v[130:131]
	s_mov_b32 m0, s63
	s_nop 0
	global_load_lds_dwordx4 v[228:229], off
	s_add_u32 s36, s36, 0x80000
	s_addc_u32 s37, s37, 0
	s_mov_b32 m0, s64
	v_lshl_add_u64 v[230:231], s[36:37], 0, v[128:129]
	ds_read_b128 v[188:191], v158 offset:32768
	ds_read_b128 v[192:195], v158 offset:33792
	ds_read_b128 v[196:199], v158 offset:34816
	ds_read_b128 v[208:211], v158 offset:35840
	ds_read_b128 v[212:215], v158 offset:36864
	ds_read_b128 v[216:219], v158 offset:37888
	ds_read_b128 v[220:223], v158 offset:38912
	ds_read_b128 v[224:227], v158 offset:39936
	global_load_lds_dwordx4 v[230:231], off
	v_lshl_add_u64 v[230:231], s[36:37], 0, v[130:131]
	s_mov_b32 m0, s65
	s_nop 0
	global_load_lds_dwordx4 v[230:231], off
	s_waitcnt vmcnt(8)
	s_waitcnt lgkmcnt(0)
	s_barrier
; #define PG8_STAGE(bufoff, gbase, voff) do { _Pragma("unroll") for (int _i = 0; _i < 2; ++_i) \
;         __builtin_amdgcn_global_load_lds((const unsigned*)((const char*)(gbase) + (voff)[_i]), (PG8_LAS unsigned*)(lds + (bufoff) + ldsw + _i * 8192), 16, 0, 0); } while (0)
; #define PG8_LDA(dst, b, h) do { _Pragma("unroll") for (int m = 0; m < 4; ++m) _Pragma("unroll") for (int k = 0; k < 2; ++k) dst[m][k] = *(const PG8_LAS bf16x8*)(lds + PG8_SA(b, h) + aoff + m * 2048 + k * 1024); } while (0)
; #define PG8_MMA(ai, bj, At, Bt) do { __builtin_amdgcn_s_setprio(1); _Pragma("unroll") for (int m = 0; m < 4; ++m) _Pragma("unroll") for (int n = 0; n < 2; ++n) _Pragma("unroll") for (int k = 0; k < 2; ++k) \
;         acc[ai][bj][m][n] = __builtin_amdgcn_mfma_f32_16x16x32_bf16(Bt[n][k], At[m][k], acc[ai][bj][m][n], 0, 0, 0); __builtin_amdgcn_s_setprio(0); } while (0)
; #define PG8_WAIT_V(n) asm volatile("s_waitcnt vmcnt(" #n ")" ::: "memory")
; #define PG8_WAIT_L(n) asm volatile("s_waitcnt lgkmcnt(" #n ")" ::: "memory")
; #define PG8_BAR __builtin_amdgcn_s_barrier()
; #define PG8_SCHED __builtin_amdgcn_sched_barrier(0)
; template <class Epi, class Sched, bool ALIGN_EPI = false, bool SP2 = false>
; __device__ __forceinline__ void gemm_phase(PG8_LAS unsigned char* lds, const Gemm g, const Sched& S, const Epi& E) {
;     ...
;         for (int t = 0; t < nt; t += 2) {
;     ...
;             PG8_WAIT_V(8); PG8_WAIT_L(0); PG8_BAR; PG8_MMA(0, 0, At, B0); PG8_MMA(0, 1, At, B1); PG8_BAR; PG8_SCHED;
;             PG8_LDA(At, 1, 1); PG8_STAGE(PG8_SB(1, 0), b3, voffB); PG8_STAGE(PG8_SB(1, 1), b3 + hstep, voffB); PG8_STAGE(PG8_SA(1, 0), a3, voffA);
;             PG8_WAIT_V(8); PG8_WAIT_L(0); PG8_BAR; PG8_MMA(1, 0, At, B0); PG8_MMA(1, 1, At, B1); PG8_BAR; PG8_SCHED;
	s_setprio 1
	s_waitcnt lgkmcnt(0)
	v_mfma_f32_16x16x32_bf16 v[124:127], v[154:157], v[188:191], v[124:127]
	v_mfma_f32_16x16x32_bf16 v[120:123], v[164:167], v[188:191], v[120:123]
	v_mfma_f32_16x16x32_bf16 v[108:111], v[154:157], v[196:199], v[108:111]
	v_mfma_f32_16x16x32_bf16 v[104:107], v[164:167], v[196:199], v[104:107]
	v_mfma_f32_16x16x32_bf16 v[92:95], v[154:157], v[212:215], v[92:95]
	v_mfma_f32_16x16x32_bf16 v[88:91], v[164:167], v[212:215], v[88:91]
	v_mfma_f32_16x16x32_bf16 v[76:79], v[154:157], v[220:223], v[76:79]
	v_mfma_f32_16x16x32_bf16 v[72:75], v[164:167], v[220:223], v[72:75]
	v_mfma_f32_16x16x32_bf16 v[124:127], v[160:163], v[192:195], v[124:127]
	v_mfma_f32_16x16x32_bf16 v[120:123], v[168:171], v[192:195], v[120:123]
	v_mfma_f32_16x16x32_bf16 v[108:111], v[160:163], v[208:211], v[108:111]
	v_mfma_f32_16x16x32_bf16 v[104:107], v[168:171], v[208:211], v[104:107]
	v_mfma_f32_16x16x32_bf16 v[92:95], v[160:163], v[216:219], v[92:95]
	v_mfma_f32_16x16x32_bf16 v[88:91], v[168:171], v[216:219], v[88:91]
	v_mfma_f32_16x16x32_bf16 v[76:79], v[160:163], v[224:227], v[76:79]
	v_mfma_f32_16x16x32_bf16 v[72:75], v[168:171], v[224:227], v[72:75]
	s_setprio 0
	s_setprio 1
	v_mfma_f32_16x16x32_bf16 v[116:119], v[172:175], v[188:191], v[116:119]
	v_mfma_f32_16x16x32_bf16 v[112:115], v[180:183], v[188:191], v[112:115]
	v_mfma_f32_16x16x32_bf16 v[100:103], v[172:175], v[196:199], v[100:103]
	v_mfma_f32_16x16x32_bf16 v[96:99], v[180:183], v[196:199], v[96:99]
	v_mfma_f32_16x16x32_bf16 v[84:87], v[172:175], v[212:215], v[84:87]
	v_mfma_f32_16x16x32_bf16 v[80:83], v[180:183], v[212:215], v[80:83]
	v_mfma_f32_16x16x32_bf16 v[68:71], v[172:175], v[220:223], v[68:71]
	v_mfma_f32_16x16x32_bf16 v[64:67], v[180:183], v[220:223], v[64:67]
	v_mfma_f32_16x16x32_bf16 v[116:119], v[176:179], v[192:195], v[116:119]
	v_mfma_f32_16x16x32_bf16 v[112:115], v[184:187], v[192:195], v[112:115]
	v_mfma_f32_16x16x32_bf16 v[100:103], v[176:179], v[208:211], v[100:103]
	v_mfma_f32_16x16x32_bf16 v[96:99], v[184:187], v[208:211], v[96:99]
	v_mfma_f32_16x16x32_bf16 v[84:87], v[176:179], v[216:219], v[84:87]
	v_mfma_f32_16x16x32_bf16 v[80:83], v[184:187], v[216:219], v[80:83]
	v_mfma_f32_16x16x32_bf16 v[68:71], v[176:179], v[224:227], v[68:71]
	v_mfma_f32_16x16x32_bf16 v[64:67], v[184:187], v[224:227], v[64:67]
	s_setprio 0
	s_barrier
	s_add_i32 s36, s61, s57
	v_lshl_add_u64 v[138:139], v[138:139], 0, s[84:85]
	s_mov_b32 m0, s36
	ds_read_b128 v[188:191], v158 offset:49152
	ds_read_b128 v[192:195], v158 offset:50176
	ds_read_b128 v[196:199], v158 offset:51200
	ds_read_b128 v[208:211], v158 offset:52224
	ds_read_b128 v[212:215], v158 offset:53248
	ds_read_b128 v[216:219], v158 offset:54272
	ds_read_b128 v[220:223], v158 offset:55296
	ds_read_b128 v[224:227], v158 offset:56320
	global_load_lds_dwordx4 v[138:139], off
	s_add_i32 m0, s36, 0x2000
	s_add_u32 s26, s26, 0x80080
	v_lshl_add_u64 v[138:139], v[146:147], 0, s[84:85]
	s_addc_u32 s27, s27, 0
	s_add_i32 s36, s72, s57
	global_load_lds_dwordx4 v[138:139], off
	v_lshl_add_u64 v[138:139], s[26:27], 0, v[140:141]
	s_mov_b32 m0, s36
	s_nop 0
	global_load_lds_dwordx4 v[138:139], off
	v_lshl_add_u64 v[138:139], s[26:27], 0, v[132:133]
	s_add_i32 m0, s36, 0x2000
	s_nop 0
	global_load_lds_dwordx4 v[138:139], off
	s_waitcnt vmcnt(4)
	s_waitcnt lgkmcnt(0)
	s_barrier
	s_setprio 1
	s_waitcnt lgkmcnt(0)
	v_mfma_f32_16x16x32_bf16 v[60:63], v[154:157], v[188:191], v[60:63]
	v_mfma_f32_16x16x32_bf16 v[56:59], v[164:167], v[188:191], v[56:59]
	v_mfma_f32_16x16x32_bf16 v[44:47], v[154:157], v[196:199], v[44:47]
	v_mfma_f32_16x16x32_bf16 v[40:43], v[164:167], v[196:199], v[40:43]
	v_mfma_f32_16x16x32_bf16 v[28:31], v[154:157], v[212:215], v[28:31]
	v_mfma_f32_16x16x32_bf16 v[24:27], v[164:167], v[212:215], v[24:27]
	v_mfma_f32_16x16x32_bf16 v[12:15], v[154:157], v[220:223], v[12:15]
	v_mfma_f32_16x16x32_bf16 v[8:11], v[164:167], v[220:223], v[8:11]
	v_mfma_f32_16x16x32_bf16 v[60:63], v[160:163], v[192:195], v[60:63]
	v_mfma_f32_16x16x32_bf16 v[56:59], v[168:171], v[192:195], v[56:59]
	v_mfma_f32_16x16x32_bf16 v[44:47], v[160:163], v[208:211], v[44:47]
	v_mfma_f32_16x16x32_bf16 v[40:43], v[168:171], v[208:211], v[40:43]
	v_mfma_f32_16x16x32_bf16 v[28:31], v[160:163], v[216:219], v[28:31]
	v_mfma_f32_16x16x32_bf16 v[24:27], v[168:171], v[216:219], v[24:27]
	v_mfma_f32_16x16x32_bf16 v[12:15], v[160:163], v[224:227], v[12:15]
	v_mfma_f32_16x16x32_bf16 v[8:11], v[168:171], v[224:227], v[8:11]
	s_setprio 0
	s_setprio 1
	v_mfma_f32_16x16x32_bf16 v[52:55], v[172:175], v[188:191], v[52:55]
	v_mfma_f32_16x16x32_bf16 v[48:51], v[180:183], v[188:191], v[48:51]
	v_mfma_f32_16x16x32_bf16 v[36:39], v[172:175], v[196:199], v[36:39]
	v_mfma_f32_16x16x32_bf16 v[32:35], v[180:183], v[196:199], v[32:35]
	v_mfma_f32_16x16x32_bf16 v[20:23], v[172:175], v[212:215], v[20:23]
	v_mfma_f32_16x16x32_bf16 v[16:19], v[180:183], v[212:215], v[16:19]
	v_mfma_f32_16x16x32_bf16 v[4:7], v[172:175], v[220:223], v[4:7]
	v_mfma_f32_16x16x32_bf16 v[0:3], v[180:183], v[220:223], v[0:3]
	v_mfma_f32_16x16x32_bf16 v[52:55], v[176:179], v[192:195], v[52:55]
	v_mfma_f32_16x16x32_bf16 v[48:51], v[184:187], v[192:195], v[48:51]
	v_mfma_f32_16x16x32_bf16 v[36:39], v[176:179], v[208:211], v[36:39]
	v_mfma_f32_16x16x32_bf16 v[32:35], v[184:187], v[208:211], v[32:35]
	v_mfma_f32_16x16x32_bf16 v[20:23], v[176:179], v[216:219], v[20:23]
	v_mfma_f32_16x16x32_bf16 v[16:19], v[184:187], v[216:219], v[16:19]
	v_mfma_f32_16x16x32_bf16 v[4:7], v[176:179], v[224:227], v[4:7]
	v_mfma_f32_16x16x32_bf16 v[0:3], v[184:187], v[224:227], v[0:3]
	s_setprio 0
	s_barrier
	s_add_i32 s56, s56, 2
	s_add_u32 s22, s22, 0x100
	s_addc_u32 s23, s23, 0
	s_add_u32 s30, s30, 0x100
	s_addc_u32 s31, s31, 0
	s_cmp_gt_u32 s56, 29
	s_cbranch_scc0 .LBB0_149
	s_and_b64 vcc, exec, s[12:13]
	s_cbranch_vccz .LBB0_152
	s_barrier

; #define MFMA16(a, b, c) __builtin_amdgcn_mfma_f32_16x16x32_bf16((a), (b), (c), 0, 0, 0)
; DI unsigned pk2(float lo, float hi) { const f32x2 v = {lo, hi}; const bf16x2_t b = __builtin_convertvector(v, bf16x2_t); return __builtin_bit_cast(unsigned, b); }
; template <int C> DI void gdn_scan_item(const Params& p, int l, int b, int h, unsigned char* smem) {
;     ...
;         for (int c = 0; c < 8; ++c) S[c] = S[c] * eg;
; #pragma unroll
;         for (int s = 0; s < KS2; ++s) {
; #pragma unroll
;             for (int c = 0; c < 8; ++c) { const bf16x8 bb = *(const bf16x8*)(VnT + (16 * c + l15) * 80 + 32 * s + 8 * gq); S[c] = MFMA16(aT[s], bb, S[c]); } }
; #pragma unroll
;         for (int c = 0; c < 8; ++c) { u32x2 o; o.x = pk2(S[c][0], S[c][1]); o.y = pk2(S[c][2], S[c][3]); *(u32x2*)(SbT + (16 * c + l15) * 144 + 16 * w + 4 * gq) = o; }
.LBB0_679:
	s_or_b64 exec, exec, s[14:15]
	s_waitcnt lgkmcnt(0)
	ds_read_b128 v[88:91], v185 offset:36864
	ds_read_b128 v[92:95], v185 offset:39424
	ds_read_b128 v[96:99], v185 offset:41984
	ds_read_b128 v[100:103], v185 offset:44544
	ds_read_b128 v[104:107], v185 offset:47104
	ds_read_b128 v[108:111], v185 offset:49664
	v_pk_mul_f32 v[34:35], v[34:35], v[154:155] op_sel_hi:[1,0]
	v_pk_mul_f32 v[32:33], v[32:33], v[154:155] op_sel_hi:[1,0]
	v_pk_mul_f32 v[38:39], v[38:39], v[154:155] op_sel_hi:[1,0]
	v_pk_mul_f32 v[36:37], v[36:37], v[154:155] op_sel_hi:[1,0]
	v_pk_mul_f32 v[42:43], v[42:43], v[154:155] op_sel_hi:[1,0]
	v_pk_mul_f32 v[40:41], v[40:41], v[154:155] op_sel_hi:[1,0]
	v_pk_mul_f32 v[46:47], v[46:47], v[154:155] op_sel_hi:[1,0]
	v_pk_mul_f32 v[44:45], v[44:45], v[154:155] op_sel_hi:[1,0]
	v_pk_mul_f32 v[50:51], v[50:51], v[154:155] op_sel_hi:[1,0]
	v_pk_mul_f32 v[48:49], v[48:49], v[154:155] op_sel_hi:[1,0]
	v_pk_mul_f32 v[54:55], v[54:55], v[154:155] op_sel_hi:[1,0]
	v_pk_mul_f32 v[52:53], v[52:53], v[154:155] op_sel_hi:[1,0]
	v_pk_mul_f32 v[58:59], v[58:59], v[154:155] op_sel_hi:[1,0]
	v_pk_mul_f32 v[56:57], v[56:57], v[154:155] op_sel_hi:[1,0]
	v_pk_mul_f32 v[62:63], v[62:63], v[154:155] op_sel_hi:[1,0]
	v_pk_mul_f32 v[60:61], v[60:61], v[154:155] op_sel_hi:[1,0]
	s_mov_b32 s4, 0x358637bd
	s_add_i32 s0, s0, 64
	s_add_i32 s17, s17, 1
	s_waitcnt vmcnt(41) lgkmcnt(5)
	v_mfma_f32_16x16x32_bf16 v[32:35], v[68:71], v[88:91], v[32:35]
	ds_read_b128 v[88:91], v185 offset:52224
	s_waitcnt lgkmcnt(5)
	v_mfma_f32_16x16x32_bf16 v[36:39], v[68:71], v[92:95], v[36:39]
	ds_read_b128 v[92:95], v185 offset:54784
	s_waitcnt lgkmcnt(5)
	v_mfma_f32_16x16x32_bf16 v[40:43], v[68:71], v[96:99], v[40:43]
	s_waitcnt lgkmcnt(4)
	v_mfma_f32_16x16x32_bf16 v[44:47], v[68:71], v[100:103], v[44:47]
	s_waitcnt lgkmcnt(3)
	v_mfma_f32_16x16x32_bf16 v[48:51], v[68:71], v[104:107], v[48:51]
	s_waitcnt lgkmcnt(2)
	v_mfma_f32_16x16x32_bf16 v[52:55], v[68:71], v[108:111], v[52:55]
	s_waitcnt lgkmcnt(1)
	v_mfma_f32_16x16x32_bf16 v[56:59], v[68:71], v[88:91], v[56:59]
	s_waitcnt lgkmcnt(0)
	v_mfma_f32_16x16x32_bf16 v[60:63], v[68:71], v[92:95], v[60:63]
	ds_read_b128 v[68:71], v185 offset:36928
	ds_read_b128 v[88:91], v185 offset:39488
	s_add_u32 s12, s12, 4
	s_addc_u32 s13, s13, 0
	s_waitcnt vmcnt(40) lgkmcnt(1)
	v_mfma_f32_16x16x32_bf16 v[32:35], v[64:67], v[68:71], v[32:35]
	ds_read_b128 v[68:71], v185 offset:42048
	ds_read_b128 v[92:95], v185 offset:44608
	ds_read_b128 v[96:99], v185 offset:47168
	s_cmpk_lg_i32 s0, 0x1000
	s_waitcnt vmcnt(24)
	s_waitcnt lgkmcnt(3)
	v_mfma_f32_16x16x32_bf16 v[36:39], v[64:67], v[88:91], v[36:39]
	ds_read_b128 v[88:91], v185 offset:49728
	ds_read_b128 v[100:103], v185 offset:52288
	ds_read_b128 v[104:107], v185 offset:54848
	s_waitcnt lgkmcnt(5)
	v_mfma_f32_16x16x32_bf16 v[40:43], v[64:67], v[68:71], v[40:43]
	v_cvt_pk_bf16_f32 v68, v32, v33
	v_cvt_pk_bf16_f32 v69, v34, v35
	s_nop 0
	v_cvt_pk_bf16_f32 v70, v36, v37
	s_waitcnt lgkmcnt(4)
	v_mfma_f32_16x16x32_bf16 v[44:47], v[64:67], v[92:95], v[44:47]
	v_cvt_pk_bf16_f32 v71, v38, v39
	ds_write2st64_b64 v186, v[68:69], v[70:71] offset1:9
	s_nop 0
	v_cvt_pk_bf16_f32 v68, v40, v41
	s_waitcnt lgkmcnt(4)
	v_mfma_f32_16x16x32_bf16 v[48:51], v[64:67], v[96:99], v[48:51]
	v_cvt_pk_bf16_f32 v69, v42, v43
	s_nop 0
	v_cvt_pk_bf16_f32 v70, v44, v45
	v_cvt_pk_bf16_f32 v71, v46, v47
	s_waitcnt lgkmcnt(3)
	v_mfma_f32_16x16x32_bf16 v[52:55], v[64:67], v[88:91], v[52:55]
	ds_write2st64_b64 v186, v[68:69], v[70:71] offset0:18 offset1:27
	s_nop 0
	v_cvt_pk_bf16_f32 v68, v48, v49
	v_cvt_pk_bf16_f32 v69, v50, v51
	s_waitcnt lgkmcnt(3)
	v_mfma_f32_16x16x32_bf16 v[56:59], v[64:67], v[100:103], v[56:59]
	v_lshlrev_b32_e32 v96, 16, v226
	s_nop 0
	v_cvt_pk_bf16_f32 v70, v52, v53
	v_cvt_pk_bf16_f32 v71, v54, v55
	s_waitcnt lgkmcnt(2)
	v_mfma_f32_16x16x32_bf16 v[60:63], v[64:67], v[104:107], v[60:63]
	ds_write2st64_b64 v186, v[68:69], v[70:71] offset0:36 offset1:45
	s_nop 0
	v_cvt_pk_bf16_f32 v64, v56, v57
	v_cvt_pk_bf16_f32 v65, v58, v59
	v_add_u32_e32 v68, 0, v179
	v_add_u32_e32 v70, 0, v180
	s_nop 1
	v_cvt_pk_bf16_f32 v66, v60, v61
	v_cvt_pk_bf16_f32 v67, v62, v63
	ds_write2st64_b64 v186, v[64:65], v[66:67] offset0:54 offset1:63
	s_waitcnt lgkmcnt(0)
	s_barrier
; DI float bf2f(unsigned short b) { return __uint_as_float(((unsigned)b) << 16); }
; DI unsigned short f2bf(float f) { unsigned u = __float_as_uint(f); u += 0x7fffu + ((u >> 16) & 1u); return (unsigned short)(u >> 16); }
; template <int C> DI void gdn_scan_item(const Params& p, int l, int b, int h, unsigned char* smem) {
;     ...
;         for (int r = 0; r < 4; ++r) { const int i = 16 * ti + 4 * gq + r; float tot = 0.f;
; #pragma unroll
;             for (int d = 0; d < NDVG; ++d) tot += RS[i * 4 + d];
;             const float rs = rsqrtf(tot * (1.0f / 128.0f) + EPS);
; #pragma unroll
;             for (int t = 0; t < TPW; ++t) { const int dv = 16 * (dvg * TPW + t) + l15; const float sz = bf2f(szr[t][r]);
;                 MIX[(size_t)(r0c + i) * KOUT + 512 + h * 128 + dv] = f2bf(a2[t][r] * rs * nw[dv] * sz); } }
	v_add_u32_e32 v66, 0, v178
	ds_read_b64 v[66:67], v66 offset:57344
	ds_read_b64 v[68:69], v68 offset:57344
	v_lshl_add_u64 v[64:65], v[126:127], 0, v[138:139]
	v_add_u32_e32 v88, 0, v181
	ds_read_b64 v[70:71], v70 offset:57344
	ds_read_b64 v[88:89], v88 offset:57344
	s_waitcnt lgkmcnt(3)
	v_mov_b32_e32 v91, v66
	s_waitcnt lgkmcnt(2)
	v_mov_b32_e32 v90, v68
	v_pk_add_f32 v[90:91], v[90:91], 0 op_sel_hi:[1,0]
	v_mov_b32_e32 v66, v69
	v_pk_add_f32 v[66:67], v[90:91], v[66:67]
	v_mov_b64_e32 v[68:69], s[4:5]
	s_brev_b32 s4, 60
	v_pk_fma_f32 v[66:67], v[66:67], s[4:5], v[68:69] op_sel_hi:[1,0,0]
	v_lshlrev_b32_e32 v91, 16, v224
	v_mul_f32_e32 v90, 0x4b800000, v67
	v_cmp_gt_f32_e32 vcc, s79, v67
	v_lshlrev_b32_e32 v97, 16, v225
	v_cndmask_b32_e32 v67, v67, v90, vcc
	v_rsq_f32_e32 v67, v67
	v_lshlrev_b32_e32 v90, 16, v223
	v_mul_f32_e32 v98, 0x45800000, v67
	v_cndmask_b32_e32 v67, v67, v98, vcc
	v_mul_f32_e32 v72, v72, v67
	v_cmp_gt_f32_e32 vcc, s79, v66
	v_mul_f32_e32 v72, v144, v72
	v_mul_f32_e32 v72, v72, v96
	v_bfe_u32 v96, v72, 16, 1
	v_add3_u32 v72, v72, v96, s59
	global_store_short_d16_hi v[64:65], v72, off
	v_mul_f32_e32 v72, v76, v67
	v_mul_f32_e32 v72, v204, v72
	v_mul_f32_e32 v72, v72, v90
	v_bfe_u32 v76, v72, 16, 1
	v_add3_u32 v72, v72, v76, s59
	global_store_short_d16_hi v[64:65], v72, off offset:32
	v_mul_f32_e32 v72, v80, v67
	v_mul_f32_e32 v72, v227, v72
	v_mul_f32_e32 v72, v72, v91
	v_bfe_u32 v76, v72, 16, 1
	v_add3_u32 v72, v72, v76, s59
	global_store_short_d16_hi v[64:65], v72, off offset:64
	v_mul_f32_e32 v72, 0x4b800000, v66
	v_mul_f32_e32 v67, v84, v67
	v_cndmask_b32_e32 v66, v66, v72, vcc
	v_mul_f32_e32 v67, v124, v67
	v_rsq_f32_e32 v66, v66
	v_mul_f32_e32 v67, v67, v97
	v_bfe_u32 v72, v67, 16, 1
	v_add3_u32 v67, v67, v72, s59
	global_store_short_d16_hi v[64:65], v67, off offset:96
	v_mul_f32_e32 v64, 0x45800000, v66
	v_cndmask_b32_e32 v66, v66, v64, vcc
	v_mul_f32_e32 v65, v73, v66
	v_lshlrev_b32_e32 v64, 16, v222
	v_mul_f32_e32 v65, v144, v65
	v_mul_f32_e32 v64, v65, v64
	v_bfe_u32 v65, v64, 16, 1
	v_add3_u32 v67, v64, v65, s59
	v_lshl_add_u64 v[64:65], v[126:127], 0, v[136:137]
	v_mul_f32_e32 v72, v77, v66
	global_store_short_d16_hi v[64:65], v67, off
	v_lshlrev_b32_e32 v67, 16, v221
	v_mul_f32_e32 v72, v204, v72
	v_mul_f32_e32 v67, v72, v67
	v_bfe_u32 v72, v67, 16, 1
	v_add3_u32 v67, v67, v72, s59
	v_mul_f32_e32 v72, v81, v66
	global_store_short_d16_hi v[64:65], v67, off offset:32
	v_lshlrev_b32_e32 v67, 16, v220
	v_mul_f32_e32 v72, v227, v72
	v_mul_f32_e32 v67, v72, v67
	v_bfe_u32 v72, v67, 16, 1
	v_add3_u32 v67, v67, v72, s59
	v_mul_f32_e32 v66, v85, v66
	global_store_short_d16_hi v[64:65], v67, off offset:64
	v_lshlrev_b32_e32 v67, 16, v219
	v_mul_f32_e32 v66, v124, v66
	v_mul_f32_e32 v66, v66, v67
	v_bfe_u32 v67, v66, 16, 1
	v_add3_u32 v66, v66, v67, s59
	global_store_short_d16_hi v[64:65], v66, off offset:96
	s_waitcnt lgkmcnt(0)
	v_mov_b32_e32 v66, v88
	v_mov_b32_e32 v67, v70
	v_pk_add_f32 v[66:67], v[66:67], 0 op_sel_hi:[1,0]
	v_mov_b32_e32 v70, v89
	v_pk_add_f32 v[66:67], v[66:67], v[70:71]
	v_lshlrev_b32_e32 v72, 16, v218
	v_pk_fma_f32 v[66:67], v[66:67], s[4:5], v[68:69] op_sel_hi:[1,0,0]
	v_lshl_add_u64 v[64:65], v[126:127], 0, v[134:135]
	v_mul_f32_e32 v68, 0x4b800000, v67
	v_cmp_gt_f32_e32 vcc, s79, v67
	v_lshlrev_b32_e32 v69, 16, v216
	v_lshlrev_b32_e32 v70, 16, v217
	v_cndmask_b32_e32 v67, v67, v68, vcc
	v_rsq_f32_e32 v67, v67
	v_lshlrev_b32_e32 v68, 16, v215
	s_mov_b64 s[4:5], 0x16000
	v_mul_f32_e32 v71, 0x45800000, v67
	v_cndmask_b32_e32 v67, v67, v71, vcc
	v_mul_f32_e32 v71, v74, v67
	v_mul_f32_e32 v71, v144, v71
	v_mul_f32_e32 v71, v71, v72
	v_bfe_u32 v72, v71, 16, 1
	v_add3_u32 v71, v71, v72, s59
	global_store_short_d16_hi v[64:65], v71, off
	v_mul_f32_e32 v71, v78, v67
	v_mul_f32_e32 v71, v204, v71
	v_mul_f32_e32 v68, v71, v68
	v_bfe_u32 v71, v68, 16, 1
	v_add3_u32 v68, v68, v71, s59
	global_store_short_d16_hi v[64:65], v68, off offset:32
	v_mul_f32_e32 v68, v82, v67
	v_mul_f32_e32 v68, v227, v68
	v_mul_f32_e32 v68, v68, v69
	v_bfe_u32 v69, v68, 16, 1
	v_add3_u32 v68, v68, v69, s59
	global_store_short_d16_hi v[64:65], v68, off offset:64
	v_mul_f32_e32 v68, 0x4b800000, v66
	v_cmp_gt_f32_e32 vcc, s79, v66
	v_mul_f32_e32 v67, v86, v67
	v_mul_f32_e32 v67, v124, v67
	v_cndmask_b32_e32 v66, v66, v68, vcc
	v_rsq_f32_e32 v66, v66
	v_mul_f32_e32 v67, v67, v70
	v_bfe_u32 v68, v67, 16, 1
	v_add3_u32 v67, v67, v68, s59
	global_store_short_d16_hi v[64:65], v67, off offset:96
	v_mul_f32_e32 v64, 0x45800000, v66
	v_cndmask_b32_e32 v66, v66, v64, vcc
	v_mul_f32_e32 v65, v75, v66
	v_lshlrev_b32_e32 v64, 16, v214
	v_mul_f32_e32 v65, v144, v65
	v_mul_f32_e32 v64, v65, v64
	v_bfe_u32 v65, v64, 16, 1
	v_add3_u32 v67, v64, v65, s59
	v_lshl_add_u64 v[64:65], v[126:127], 0, v[132:133]
	v_mul_f32_e32 v68, v79, v66
	global_store_short_d16_hi v[64:65], v67, off
	v_lshlrev_b32_e32 v67, 16, v208
	v_mul_f32_e32 v68, v204, v68
	v_mul_f32_e32 v67, v68, v67
	v_bfe_u32 v68, v67, 16, 1
	v_add3_u32 v67, v67, v68, s59
	v_mul_f32_e32 v68, v83, v66
	global_store_short_d16_hi v[64:65], v67, off offset:32
	v_lshlrev_b32_e32 v67, 16, v194
	v_mul_f32_e32 v68, v227, v68
	v_mul_f32_e32 v67, v68, v67
	v_bfe_u32 v68, v67, 16, 1
	v_add3_u32 v67, v67, v68, s59
	v_mul_f32_e32 v66, v87, v66
	global_store_short_d16_hi v[64:65], v67, off offset:64
	v_lshlrev_b32_e32 v67, 16, v191
	v_mul_f32_e32 v66, v124, v66
	v_mul_f32_e32 v66, v66, v67
	v_bfe_u32 v67, v66, 16, 1
	v_add3_u32 v66, v66, v67, s59
	v_lshl_add_u64 v[128:129], v[128:129], 0, s[4:5]
	v_lshl_add_u64 v[130:131], v[130:131], 0, s[4:5]
	global_store_short_d16_hi v[64:65], v66, off offset:96
	s_cbranch_scc0 .LBB0_684

; #define PG8_STAGE(bufoff, gbase, voff) do { _Pragma("unroll") for (int _i = 0; _i < 2; ++_i) \
;         __builtin_amdgcn_global_load_lds((const unsigned*)((const char*)(gbase) + (voff)[_i]), (PG8_LAS unsigned*)(lds + (bufoff) + ldsw + _i * 8192), 16, 0, 0); } while (0)
; #define PG8_LDA(dst, b, h) do { _Pragma("unroll") for (int m = 0; m < 4; ++m) _Pragma("unroll") for (int k = 0; k < 2; ++k) dst[m][k] = *(const PG8_LAS bf16x8*)(lds + PG8_SA(b, h) + aoff + m * 2048 + k * 1024); } while (0)
; #define PG8_LDB(dst, b, h) do { _Pragma("unroll") for (int n = 0; n < 2; ++n) _Pragma("unroll") for (int k = 0; k < 2; ++k) dst[n][k] = *(const PG8_LAS bf16x8*)(lds + PG8_SB(b, h) + boff + n * 2048 + k * 1024); } while (0)
; #define PG8_MMA(ai, bj, At, Bt) do { __builtin_amdgcn_s_setprio(1); _Pragma("unroll") for (int m = 0; m < 4; ++m) _Pragma("unroll") for (int n = 0; n < 2; ++n) _Pragma("unroll") for (int k = 0; k < 2; ++k) \
;         acc[ai][bj][m][n] = __builtin_amdgcn_mfma_f32_16x16x32_bf16(Bt[n][k], At[m][k], acc[ai][bj][m][n], 0, 0, 0); __builtin_amdgcn_s_setprio(0); } while (0)
; #define PG8_WAIT_V(n) asm volatile("s_waitcnt vmcnt(" #n ")" ::: "memory")
; #define PG8_WAIT_L(n) asm volatile("s_waitcnt lgkmcnt(" #n ")" ::: "memory")
; #define PG8_BAR __builtin_amdgcn_s_barrier()
; #define PG8_SCHED __builtin_amdgcn_sched_barrier(0)
; template <class Epi, class Sched, bool ALIGN_EPI = false, bool SP2 = false>
; __device__ __forceinline__ void gemm_phase(PG8_LAS unsigned char* lds, const Gemm g, const Sched& S, const Epi& E) {
;     ...
;             PG8_LDB(B0, 0, 0); PG8_LDB(B1, 0, 1); PG8_SCHED; PG8_LDA(At, 0, 0); PG8_STAGE(PG8_SA(1, 1), a1 + hstep, voffA);
;             PG8_WAIT_V(8); PG8_WAIT_L(0); PG8_BAR; PG8_MMA(0, 0, At, B0); PG8_MMA(0, 1, At, B1); PG8_BAR; PG8_SCHED;
;             PG8_LDA(At, 0, 1); PG8_STAGE(PG8_SB(0, 0), b2, voffB); PG8_STAGE(PG8_SB(0, 1), b2 + hstep, voffB); PG8_STAGE(PG8_SA(0, 0), a2, voffA);
;             PG8_WAIT_V(8); PG8_WAIT_L(0); PG8_BAR; PG8_MMA(1, 0, At, B0); PG8_MMA(1, 1, At, B1); PG8_BAR; PG8_SCHED;
.LBB0_816:
	s_add_u32 s54, s48, 0x100
	s_addc_u32 s55, s49, 0
	s_add_i32 s61, 0, 0x10000
	s_cmp_eq_u32 s56, 28
	s_cselect_b32 s65, s14, s55
	s_cselect_b32 s64, s15, s54
	v_add_u32_e32 v140, s61, v151
	s_cselect_b32 s63, s21, s31
	s_cselect_b32 s62, s23, s30
	s_add_i32 s78, 0, 0x14000
	ds_read_b128 v[136:139], v140
	ds_read_b128 v[146:149], v140 offset:1024
	ds_read_b128 v[154:157], v140 offset:2048
	ds_read_b128 v[160:163], v140 offset:3072
	v_add_u32_e32 v140, s78, v151
	ds_read_b128 v[164:167], v140
	ds_read_b128 v[168:171], v140 offset:1024
	ds_read_b128 v[172:175], v140 offset:2048
	ds_read_b128 v[176:179], v140 offset:3072
	v_lshl_add_u64 v[220:221], s[48:49], 0, v[132:133]
	s_add_i32 m0, s72, 0xc000
	ds_read_b128 v[180:183], v158
	ds_read_b128 v[184:187], v158 offset:1024
	ds_read_b128 v[188:191], v158 offset:2048
	ds_read_b128 v[192:195], v158 offset:3072
	ds_read_b128 v[196:199], v158 offset:4096
	ds_read_b128 v[208:211], v158 offset:5120
	ds_read_b128 v[212:215], v158 offset:6144
	ds_read_b128 v[216:219], v158 offset:7168
	global_load_lds_dwordx4 v[220:221], off
	v_lshl_add_u64 v[220:221], s[48:49], 0, v[134:135]
	s_add_i32 m0, s72, 0xe000
	s_nop 0
	global_load_lds_dwordx4 v[220:221], off
	v_lshl_add_u64 v[220:221], v[224:225], 0, s[84:85]
	s_mov_b32 m0, s91
	s_nop 0
	global_load_lds_dwordx4 v[220:221], off
	v_lshl_add_u64 v[220:221], v[226:227], 0, s[84:85]
	s_mov_b32 m0, s92
	s_nop 0
	global_load_lds_dwordx4 v[220:221], off
	s_waitcnt vmcnt(8)
	s_waitcnt lgkmcnt(0)
	s_barrier
	s_setprio 1
	s_waitcnt lgkmcnt(0)
	v_mfma_f32_16x16x32_bf16 v[124:127], v[136:139], v[180:183], v[124:127]
	v_mfma_f32_16x16x32_bf16 v[120:123], v[154:157], v[180:183], v[120:123]
	v_mfma_f32_16x16x32_bf16 v[108:111], v[136:139], v[188:191], v[108:111]
	v_mfma_f32_16x16x32_bf16 v[104:107], v[154:157], v[188:191], v[104:107]
	v_mfma_f32_16x16x32_bf16 v[92:95], v[136:139], v[196:199], v[92:95]
	v_mfma_f32_16x16x32_bf16 v[88:91], v[154:157], v[196:199], v[88:91]
	v_mfma_f32_16x16x32_bf16 v[76:79], v[136:139], v[212:215], v[76:79]
	v_mfma_f32_16x16x32_bf16 v[72:75], v[154:157], v[212:215], v[72:75]
	v_mfma_f32_16x16x32_bf16 v[124:127], v[146:149], v[184:187], v[124:127]
	v_mfma_f32_16x16x32_bf16 v[120:123], v[160:163], v[184:187], v[120:123]
	v_mfma_f32_16x16x32_bf16 v[108:111], v[146:149], v[192:195], v[108:111]
	v_mfma_f32_16x16x32_bf16 v[104:107], v[160:163], v[192:195], v[104:107]
	v_mfma_f32_16x16x32_bf16 v[92:95], v[146:149], v[208:211], v[92:95]
	v_mfma_f32_16x16x32_bf16 v[88:91], v[160:163], v[208:211], v[88:91]
	v_mfma_f32_16x16x32_bf16 v[76:79], v[146:149], v[216:219], v[76:79]
	v_mfma_f32_16x16x32_bf16 v[72:75], v[160:163], v[216:219], v[72:75]
	s_setprio 0
	s_setprio 1
	v_mfma_f32_16x16x32_bf16 v[116:119], v[164:167], v[180:183], v[116:119]
	v_mfma_f32_16x16x32_bf16 v[112:115], v[172:175], v[180:183], v[112:115]
	v_mfma_f32_16x16x32_bf16 v[100:103], v[164:167], v[188:191], v[100:103]
	v_mfma_f32_16x16x32_bf16 v[96:99], v[172:175], v[188:191], v[96:99]
	v_mfma_f32_16x16x32_bf16 v[84:87], v[164:167], v[196:199], v[84:87]
	v_mfma_f32_16x16x32_bf16 v[80:83], v[172:175], v[196:199], v[80:83]
	v_mfma_f32_16x16x32_bf16 v[68:71], v[164:167], v[212:215], v[68:71]
	v_mfma_f32_16x16x32_bf16 v[64:67], v[172:175], v[212:215], v[64:67]
	v_mfma_f32_16x16x32_bf16 v[116:119], v[168:171], v[184:187], v[116:119]
	v_mfma_f32_16x16x32_bf16 v[112:115], v[176:179], v[184:187], v[112:115]
	v_mfma_f32_16x16x32_bf16 v[100:103], v[168:171], v[192:195], v[100:103]
	v_mfma_f32_16x16x32_bf16 v[96:99], v[176:179], v[192:195], v[96:99]
	v_mfma_f32_16x16x32_bf16 v[84:87], v[168:171], v[208:211], v[84:87]
	v_mfma_f32_16x16x32_bf16 v[80:83], v[176:179], v[208:211], v[80:83]
	v_mfma_f32_16x16x32_bf16 v[68:71], v[168:171], v[216:219], v[68:71]
	v_mfma_f32_16x16x32_bf16 v[64:67], v[176:179], v[216:219], v[64:67]
	s_setprio 0
	s_barrier
	s_add_i32 s48, s61, s71
	v_lshl_add_u64 v[220:221], s[62:63], 0, v[130:131]
	s_mov_b32 m0, s48
	ds_read_b128 v[180:183], v158 offset:16384
	ds_read_b128 v[184:187], v158 offset:17408
	ds_read_b128 v[188:191], v158 offset:18432
	ds_read_b128 v[192:195], v158 offset:19456
	ds_read_b128 v[196:199], v158 offset:20480
	ds_read_b128 v[208:211], v158 offset:21504
	ds_read_b128 v[212:215], v158 offset:22528
	ds_read_b128 v[216:219], v158 offset:23552
	global_load_lds_dwordx4 v[220:221], off
	s_add_i32 m0, s48, 0x2000
	s_add_u32 s48, s62, 0x80000
	v_lshl_add_u64 v[222:223], s[62:63], 0, v[128:129]
	s_addc_u32 s49, s63, 0
	s_add_i32 s61, s78, s71
	global_load_lds_dwordx4 v[222:223], off
	v_lshl_add_u64 v[224:225], s[48:49], 0, v[130:131]
	s_mov_b32 m0, s61
	s_nop 0
	global_load_lds_dwordx4 v[224:225], off
	v_lshl_add_u64 v[224:225], s[48:49], 0, v[128:129]
	s_add_i32 m0, s61, 0x2000
	s_nop 0
	global_load_lds_dwordx4 v[224:225], off
	s_waitcnt vmcnt(4)
	s_waitcnt lgkmcnt(0)
	s_barrier
; #define PG8_STAGE(bufoff, gbase, voff) do { _Pragma("unroll") for (int _i = 0; _i < 2; ++_i) \
;         __builtin_amdgcn_global_load_lds((const unsigned*)((const char*)(gbase) + (voff)[_i]), (PG8_LAS unsigned*)(lds + (bufoff) + ldsw + _i * 8192), 16, 0, 0); } while (0)
; #define PG8_LDA(dst, b, h) do { _Pragma("unroll") for (int m = 0; m < 4; ++m) _Pragma("unroll") for (int k = 0; k < 2; ++k) dst[m][k] = *(const PG8_LAS bf16x8*)(lds + PG8_SA(b, h) + aoff + m * 2048 + k * 1024); } while (0)
; #define PG8_LDB(dst, b, h) do { _Pragma("unroll") for (int n = 0; n < 2; ++n) _Pragma("unroll") for (int k = 0; k < 2; ++k) dst[n][k] = *(const PG8_LAS bf16x8*)(lds + PG8_SB(b, h) + boff + n * 2048 + k * 1024); } while (0)
; #define PG8_MMA(ai, bj, At, Bt) do { __builtin_amdgcn_s_setprio(1); _Pragma("unroll") for (int m = 0; m < 4; ++m) _Pragma("unroll") for (int n = 0; n < 2; ++n) _Pragma("unroll") for (int k = 0; k < 2; ++k) \
;         acc[ai][bj][m][n] = __builtin_amdgcn_mfma_f32_16x16x32_bf16(Bt[n][k], At[m][k], acc[ai][bj][m][n], 0, 0, 0); __builtin_amdgcn_s_setprio(0); } while (0)
; #define PG8_WAIT_V(n) asm volatile("s_waitcnt vmcnt(" #n ")" ::: "memory")
; #define PG8_WAIT_L(n) asm volatile("s_waitcnt lgkmcnt(" #n ")" ::: "memory")
; #define PG8_BAR __builtin_amdgcn_s_barrier()
; #define PG8_SCHED __builtin_amdgcn_sched_barrier(0)
; template <class Epi, class Sched, bool ALIGN_EPI = false, bool SP2 = false>
; __device__ __forceinline__ void gemm_phase(PG8_LAS unsigned char* lds, const Gemm g, const Sched& S, const Epi& E) {
;     ...
;             PG8_WAIT_V(8); PG8_WAIT_L(0); PG8_BAR; PG8_MMA(1, 0, At, B0); PG8_MMA(1, 1, At, B1); PG8_BAR; PG8_SCHED;
;             PG8_LDB(B0, 1, 0); PG8_LDB(B1, 1, 1); PG8_SCHED; PG8_LDA(At, 1, 0); PG8_STAGE(PG8_SA(0, 1), a2 + hstep, voffA);
;             PG8_WAIT_V(8); PG8_WAIT_L(0); PG8_BAR; PG8_MMA(0, 0, At, B0); PG8_MMA(0, 1, At, B1); PG8_BAR; PG8_SCHED;
	s_setprio 1
	s_waitcnt lgkmcnt(0)
	v_mfma_f32_16x16x32_bf16 v[60:63], v[136:139], v[180:183], v[60:63]
	v_mfma_f32_16x16x32_bf16 v[56:59], v[154:157], v[180:183], v[56:59]
	v_mfma_f32_16x16x32_bf16 v[44:47], v[136:139], v[188:191], v[44:47]
	v_mfma_f32_16x16x32_bf16 v[40:43], v[154:157], v[188:191], v[40:43]
	v_mfma_f32_16x16x32_bf16 v[28:31], v[136:139], v[196:199], v[28:31]
	v_mfma_f32_16x16x32_bf16 v[24:27], v[154:157], v[196:199], v[24:27]
	v_mfma_f32_16x16x32_bf16 v[12:15], v[136:139], v[212:215], v[12:15]
	v_mfma_f32_16x16x32_bf16 v[8:11], v[154:157], v[212:215], v[8:11]
	v_mfma_f32_16x16x32_bf16 v[60:63], v[146:149], v[184:187], v[60:63]
	v_mfma_f32_16x16x32_bf16 v[56:59], v[160:163], v[184:187], v[56:59]
	v_mfma_f32_16x16x32_bf16 v[44:47], v[146:149], v[192:195], v[44:47]
	v_mfma_f32_16x16x32_bf16 v[40:43], v[160:163], v[192:195], v[40:43]
	v_mfma_f32_16x16x32_bf16 v[28:31], v[146:149], v[208:211], v[28:31]
	v_mfma_f32_16x16x32_bf16 v[24:27], v[160:163], v[208:211], v[24:27]
	v_mfma_f32_16x16x32_bf16 v[12:15], v[146:149], v[216:219], v[12:15]
	v_mfma_f32_16x16x32_bf16 v[8:11], v[160:163], v[216:219], v[8:11]
	s_setprio 0
	s_setprio 1
	v_mfma_f32_16x16x32_bf16 v[52:55], v[164:167], v[180:183], v[52:55]
	v_mfma_f32_16x16x32_bf16 v[48:51], v[172:175], v[180:183], v[48:51]
	v_mfma_f32_16x16x32_bf16 v[36:39], v[164:167], v[188:191], v[36:39]
	v_mfma_f32_16x16x32_bf16 v[32:35], v[172:175], v[188:191], v[32:35]
	v_mfma_f32_16x16x32_bf16 v[20:23], v[164:167], v[196:199], v[20:23]
	v_mfma_f32_16x16x32_bf16 v[16:19], v[172:175], v[196:199], v[16:19]
	v_mfma_f32_16x16x32_bf16 v[4:7], v[164:167], v[212:215], v[4:7]
	v_mfma_f32_16x16x32_bf16 v[0:3], v[172:175], v[212:215], v[0:3]
	v_mfma_f32_16x16x32_bf16 v[52:55], v[168:171], v[184:187], v[52:55]
	v_mfma_f32_16x16x32_bf16 v[48:51], v[176:179], v[184:187], v[48:51]
	v_mfma_f32_16x16x32_bf16 v[36:39], v[168:171], v[192:195], v[36:39]
	v_mfma_f32_16x16x32_bf16 v[32:35], v[176:179], v[192:195], v[32:35]
	v_mfma_f32_16x16x32_bf16 v[20:23], v[168:171], v[208:211], v[20:23]
	v_mfma_f32_16x16x32_bf16 v[16:19], v[176:179], v[208:211], v[16:19]
	v_mfma_f32_16x16x32_bf16 v[4:7], v[168:171], v[216:219], v[4:7]
	v_mfma_f32_16x16x32_bf16 v[0:3], v[176:179], v[216:219], v[0:3]
	s_setprio 0
	s_barrier
	s_add_i32 s61, 0, 0x18000
	v_add_u32_e32 v140, s61, v151
	s_add_i32 s78, 0, 0x1c000
	ds_read_b128 v[136:139], v140
	ds_read_b128 v[146:149], v140 offset:1024
	ds_read_b128 v[154:157], v140 offset:2048
	ds_read_b128 v[160:163], v140 offset:3072
	v_add_u32_e32 v140, s78, v151
	ds_read_b128 v[164:167], v140
	ds_read_b128 v[168:171], v140 offset:1024
	ds_read_b128 v[172:175], v140 offset:2048
	ds_read_b128 v[176:179], v140 offset:3072
	v_lshl_add_u64 v[224:225], s[64:65], 0, v[130:131]
	s_mov_b32 m0, s72
	s_nop 0
	global_load_lds_dwordx4 v[224:225], off
	v_lshl_add_u64 v[226:227], s[64:65], 0, v[128:129]
	s_mov_b32 m0, s73
	s_nop 0
	global_load_lds_dwordx4 v[226:227], off
	s_add_u32 s48, s64, 0x80000
	s_addc_u32 s49, s65, 0
	s_mov_b32 m0, s76
	v_lshl_add_u64 v[228:229], s[48:49], 0, v[130:131]
	ds_read_b128 v[180:183], v158 offset:32768
	ds_read_b128 v[184:187], v158 offset:33792
	ds_read_b128 v[188:191], v158 offset:34816
	ds_read_b128 v[192:195], v158 offset:35840
	ds_read_b128 v[196:199], v158 offset:36864
	ds_read_b128 v[208:211], v158 offset:37888
	ds_read_b128 v[212:215], v158 offset:38912
	ds_read_b128 v[216:219], v158 offset:39936
	global_load_lds_dwordx4 v[228:229], off
	v_lshl_add_u64 v[228:229], s[48:49], 0, v[128:129]
	s_mov_b32 m0, s90
	s_nop 0
	global_load_lds_dwordx4 v[228:229], off
	s_waitcnt vmcnt(8)
	s_waitcnt lgkmcnt(0)
	s_barrier
; #define PG8_STAGE(bufoff, gbase, voff) do { _Pragma("unroll") for (int _i = 0; _i < 2; ++_i) \
;         __builtin_amdgcn_global_load_lds((const unsigned*)((const char*)(gbase) + (voff)[_i]), (PG8_LAS unsigned*)(lds + (bufoff) + ldsw + _i * 8192), 16, 0, 0); } while (0)
; #define PG8_LDA(dst, b, h) do { _Pragma("unroll") for (int m = 0; m < 4; ++m) _Pragma("unroll") for (int k = 0; k < 2; ++k) dst[m][k] = *(const PG8_LAS bf16x8*)(lds + PG8_SA(b, h) + aoff + m * 2048 + k * 1024); } while (0)
; #define PG8_MMA(ai, bj, At, Bt) do { __builtin_amdgcn_s_setprio(1); _Pragma("unroll") for (int m = 0; m < 4; ++m) _Pragma("unroll") for (int n = 0; n < 2; ++n) _Pragma("unroll") for (int k = 0; k < 2; ++k) \
;         acc[ai][bj][m][n] = __builtin_amdgcn_mfma_f32_16x16x32_bf16(Bt[n][k], At[m][k], acc[ai][bj][m][n], 0, 0, 0); __builtin_amdgcn_s_setprio(0); } while (0)
; #define PG8_WAIT_V(n) asm volatile("s_waitcnt vmcnt(" #n ")" ::: "memory")
; #define PG8_WAIT_L(n) asm volatile("s_waitcnt lgkmcnt(" #n ")" ::: "memory")
; #define PG8_BAR __builtin_amdgcn_s_barrier()
; #define PG8_SCHED __builtin_amdgcn_sched_barrier(0)
; template <class Epi, class Sched, bool ALIGN_EPI = false, bool SP2 = false>
; __device__ __forceinline__ void gemm_phase(PG8_LAS unsigned char* lds, const Gemm g, const Sched& S, const Epi& E) {
;     ...
;         for (int t = 0; t < nt; t += 2) {
;     ...
;             PG8_WAIT_V(8); PG8_WAIT_L(0); PG8_BAR; PG8_MMA(0, 0, At, B0); PG8_MMA(0, 1, At, B1); PG8_BAR; PG8_SCHED;
;             PG8_LDA(At, 1, 1); PG8_STAGE(PG8_SB(1, 0), b3, voffB); PG8_STAGE(PG8_SB(1, 1), b3 + hstep, voffB); PG8_STAGE(PG8_SA(1, 0), a3, voffA);
;             PG8_WAIT_V(8); PG8_WAIT_L(0); PG8_BAR; PG8_MMA(1, 0, At, B0); PG8_MMA(1, 1, At, B1); PG8_BAR; PG8_SCHED;
	s_setprio 1
	s_waitcnt lgkmcnt(0)
	v_mfma_f32_16x16x32_bf16 v[124:127], v[136:139], v[180:183], v[124:127]
	v_mfma_f32_16x16x32_bf16 v[120:123], v[154:157], v[180:183], v[120:123]
	v_mfma_f32_16x16x32_bf16 v[108:111], v[136:139], v[188:191], v[108:111]
	v_mfma_f32_16x16x32_bf16 v[104:107], v[154:157], v[188:191], v[104:107]
	v_mfma_f32_16x16x32_bf16 v[92:95], v[136:139], v[196:199], v[92:95]
	v_mfma_f32_16x16x32_bf16 v[88:91], v[154:157], v[196:199], v[88:91]
	v_mfma_f32_16x16x32_bf16 v[76:79], v[136:139], v[212:215], v[76:79]
	v_mfma_f32_16x16x32_bf16 v[72:75], v[154:157], v[212:215], v[72:75]
	v_mfma_f32_16x16x32_bf16 v[124:127], v[146:149], v[184:187], v[124:127]
	v_mfma_f32_16x16x32_bf16 v[120:123], v[160:163], v[184:187], v[120:123]
	v_mfma_f32_16x16x32_bf16 v[108:111], v[146:149], v[192:195], v[108:111]
	v_mfma_f32_16x16x32_bf16 v[104:107], v[160:163], v[192:195], v[104:107]
	v_mfma_f32_16x16x32_bf16 v[92:95], v[146:149], v[208:211], v[92:95]
	v_mfma_f32_16x16x32_bf16 v[88:91], v[160:163], v[208:211], v[88:91]
	v_mfma_f32_16x16x32_bf16 v[76:79], v[146:149], v[216:219], v[76:79]
	v_mfma_f32_16x16x32_bf16 v[72:75], v[160:163], v[216:219], v[72:75]
	s_setprio 0
	s_setprio 1
	v_mfma_f32_16x16x32_bf16 v[116:119], v[164:167], v[180:183], v[116:119]
	v_mfma_f32_16x16x32_bf16 v[112:115], v[172:175], v[180:183], v[112:115]
	v_mfma_f32_16x16x32_bf16 v[100:103], v[164:167], v[188:191], v[100:103]
	v_mfma_f32_16x16x32_bf16 v[96:99], v[172:175], v[188:191], v[96:99]
	v_mfma_f32_16x16x32_bf16 v[84:87], v[164:167], v[196:199], v[84:87]
	v_mfma_f32_16x16x32_bf16 v[80:83], v[172:175], v[196:199], v[80:83]
	v_mfma_f32_16x16x32_bf16 v[68:71], v[164:167], v[212:215], v[68:71]
	v_mfma_f32_16x16x32_bf16 v[64:67], v[172:175], v[212:215], v[64:67]
	v_mfma_f32_16x16x32_bf16 v[116:119], v[168:171], v[184:187], v[116:119]
	v_mfma_f32_16x16x32_bf16 v[112:115], v[176:179], v[184:187], v[112:115]
	v_mfma_f32_16x16x32_bf16 v[100:103], v[168:171], v[192:195], v[100:103]
	v_mfma_f32_16x16x32_bf16 v[96:99], v[176:179], v[192:195], v[96:99]
	v_mfma_f32_16x16x32_bf16 v[84:87], v[168:171], v[208:211], v[84:87]
	v_mfma_f32_16x16x32_bf16 v[80:83], v[176:179], v[208:211], v[80:83]
	v_mfma_f32_16x16x32_bf16 v[68:71], v[168:171], v[216:219], v[68:71]
	v_mfma_f32_16x16x32_bf16 v[64:67], v[176:179], v[216:219], v[64:67]
	s_setprio 0
	s_barrier
	s_add_i32 s48, s61, s71
	v_lshl_add_u64 v[220:221], v[220:221], 0, s[84:85]
	s_mov_b32 m0, s48
	ds_read_b128 v[180:183], v158 offset:49152
	ds_read_b128 v[184:187], v158 offset:50176
	ds_read_b128 v[188:191], v158 offset:51200
	ds_read_b128 v[192:195], v158 offset:52224
	ds_read_b128 v[196:199], v158 offset:53248
	ds_read_b128 v[208:211], v158 offset:54272
	ds_read_b128 v[212:215], v158 offset:55296
	ds_read_b128 v[216:219], v158 offset:56320
	global_load_lds_dwordx4 v[220:221], off
	s_add_i32 m0, s48, 0x2000
	s_add_u32 s48, s62, 0x80080
	v_lshl_add_u64 v[220:221], v[222:223], 0, s[84:85]
	s_addc_u32 s49, s63, 0
	s_add_i32 s61, s78, s71
	global_load_lds_dwordx4 v[220:221], off
	v_lshl_add_u64 v[220:221], s[48:49], 0, v[130:131]
	s_mov_b32 m0, s61
	s_nop 0
	global_load_lds_dwordx4 v[220:221], off
	v_lshl_add_u64 v[220:221], s[48:49], 0, v[128:129]
	s_add_i32 m0, s61, 0x2000
	s_nop 0
	global_load_lds_dwordx4 v[220:221], off
	s_waitcnt vmcnt(4)
	s_waitcnt lgkmcnt(0)
	s_barrier
	s_setprio 1
	s_waitcnt lgkmcnt(0)
	v_mfma_f32_16x16x32_bf16 v[60:63], v[136:139], v[180:183], v[60:63]
	v_mfma_f32_16x16x32_bf16 v[56:59], v[154:157], v[180:183], v[56:59]
	v_mfma_f32_16x16x32_bf16 v[44:47], v[136:139], v[188:191], v[44:47]
	v_mfma_f32_16x16x32_bf16 v[40:43], v[154:157], v[188:191], v[40:43]
	v_mfma_f32_16x16x32_bf16 v[28:31], v[136:139], v[196:199], v[28:31]
	v_mfma_f32_16x16x32_bf16 v[24:27], v[154:157], v[196:199], v[24:27]
	v_mfma_f32_16x16x32_bf16 v[12:15], v[136:139], v[212:215], v[12:15]
	v_mfma_f32_16x16x32_bf16 v[8:11], v[154:157], v[212:215], v[8:11]
	v_mfma_f32_16x16x32_bf16 v[60:63], v[146:149], v[184:187], v[60:63]
	v_mfma_f32_16x16x32_bf16 v[56:59], v[160:163], v[184:187], v[56:59]
	v_mfma_f32_16x16x32_bf16 v[44:47], v[146:149], v[192:195], v[44:47]
	v_mfma_f32_16x16x32_bf16 v[40:43], v[160:163], v[192:195], v[40:43]
	v_mfma_f32_16x16x32_bf16 v[28:31], v[146:149], v[208:211], v[28:31]
	v_mfma_f32_16x16x32_bf16 v[24:27], v[160:163], v[208:211], v[24:27]
	v_mfma_f32_16x16x32_bf16 v[12:15], v[146:149], v[216:219], v[12:15]
	v_mfma_f32_16x16x32_bf16 v[8:11], v[160:163], v[216:219], v[8:11]
	s_setprio 0
	s_setprio 1
	v_mfma_f32_16x16x32_bf16 v[52:55], v[164:167], v[180:183], v[52:55]
	v_mfma_f32_16x16x32_bf16 v[48:51], v[172:175], v[180:183], v[48:51]
	v_mfma_f32_16x16x32_bf16 v[36:39], v[164:167], v[188:191], v[36:39]
	v_mfma_f32_16x16x32_bf16 v[32:35], v[172:175], v[188:191], v[32:35]
	v_mfma_f32_16x16x32_bf16 v[20:23], v[164:167], v[196:199], v[20:23]
	v_mfma_f32_16x16x32_bf16 v[16:19], v[172:175], v[196:199], v[16:19]
	v_mfma_f32_16x16x32_bf16 v[4:7], v[164:167], v[212:215], v[4:7]
	v_mfma_f32_16x16x32_bf16 v[0:3], v[172:175], v[212:215], v[0:3]
	v_mfma_f32_16x16x32_bf16 v[52:55], v[168:171], v[184:187], v[52:55]
	v_mfma_f32_16x16x32_bf16 v[48:51], v[176:179], v[184:187], v[48:51]
	v_mfma_f32_16x16x32_bf16 v[36:39], v[168:171], v[192:195], v[36:39]
	v_mfma_f32_16x16x32_bf16 v[32:35], v[176:179], v[192:195], v[32:35]
	v_mfma_f32_16x16x32_bf16 v[20:23], v[168:171], v[208:211], v[20:23]
	v_mfma_f32_16x16x32_bf16 v[16:19], v[176:179], v[208:211], v[16:19]
	v_mfma_f32_16x16x32_bf16 v[4:7], v[168:171], v[216:219], v[4:7]
	v_mfma_f32_16x16x32_bf16 v[0:3], v[176:179], v[216:219], v[0:3]
	s_setprio 0
	s_barrier
	s_add_i32 s56, s56, 2
	s_add_u32 s30, s30, 0x100
	s_addc_u32 s31, s31, 0
	s_cmp_gt_u32 s56, 29
	s_mov_b64 s[48:49], s[54:55]
	s_cbranch_scc0 .LBB0_816
	s_and_b64 vcc, exec, s[18:19]
	s_cbranch_vccz .LBB0_819
	s_barrier

; #define PG8_STAGE(bufoff, gbase, voff) do { _Pragma("unroll") for (int _i = 0; _i < 2; ++_i) \
;         __builtin_amdgcn_global_load_lds((const unsigned*)((const char*)(gbase) + (voff)[_i]), (PG8_LAS unsigned*)(lds + (bufoff) + ldsw + _i * 8192), 16, 0, 0); } while (0)
; #define PG8_LDA(dst, b, h) do { _Pragma("unroll") for (int m = 0; m < 4; ++m) _Pragma("unroll") for (int k = 0; k < 2; ++k) dst[m][k] = *(const PG8_LAS bf16x8*)(lds + PG8_SA(b, h) + aoff + m * 2048 + k * 1024); } while (0)
; #define PG8_LDB(dst, b, h) do { _Pragma("unroll") for (int n = 0; n < 2; ++n) _Pragma("unroll") for (int k = 0; k < 2; ++k) dst[n][k] = *(const PG8_LAS bf16x8*)(lds + PG8_SB(b, h) + boff + n * 2048 + k * 1024); } while (0)
; #define PG8_MMA(ai, bj, At, Bt) do { __builtin_amdgcn_s_setprio(1); _Pragma("unroll") for (int m = 0; m < 4; ++m) _Pragma("unroll") for (int n = 0; n < 2; ++n) _Pragma("unroll") for (int k = 0; k < 2; ++k) \
;         acc[ai][bj][m][n] = __builtin_amdgcn_mfma_f32_16x16x32_bf16(Bt[n][k], At[m][k], acc[ai][bj][m][n], 0, 0, 0); __builtin_amdgcn_s_setprio(0); } while (0)
; #define PG8_WAIT_V(n) asm volatile("s_waitcnt vmcnt(" #n ")" ::: "memory")
; #define PG8_WAIT_L(n) asm volatile("s_waitcnt lgkmcnt(" #n ")" ::: "memory")
; #define PG8_BAR __builtin_amdgcn_s_barrier()
; #define PG8_SCHED __builtin_amdgcn_sched_barrier(0)
; template <class Epi, class Sched, bool ALIGN_EPI = false, bool SP2 = false>
; __device__ __forceinline__ void gemm_phase(PG8_LAS unsigned char* lds, const Gemm g, const Sched& S, const Epi& E) {
;     ...
;             PG8_LDB(B0, 0, 0); PG8_LDB(B1, 0, 1); PG8_SCHED; PG8_LDA(At, 0, 0); PG8_STAGE(PG8_SA(1, 1), a1 + hstep, voffA);
;             PG8_WAIT_V(8); PG8_WAIT_L(0); PG8_BAR; PG8_MMA(0, 0, At, B0); PG8_MMA(0, 1, At, B1); PG8_BAR; PG8_SCHED;
;             PG8_LDA(At, 0, 1); PG8_STAGE(PG8_SB(0, 0), b2, voffB); PG8_STAGE(PG8_SB(0, 1), b2 + hstep, voffB); PG8_STAGE(PG8_SA(0, 0), a2, voffA);
;             PG8_WAIT_V(8); PG8_WAIT_L(0); PG8_BAR; PG8_MMA(1, 0, At, B0); PG8_MMA(1, 1, At, B1); PG8_BAR; PG8_SCHED;
.LBB0_1010:
	s_add_u32 s26, s22, 0xfff80080
	s_addc_u32 s27, s23, -1
	s_add_i32 s43, 0, 0x10000
	s_cmp_eq_u32 s76, 28
	s_cselect_b32 s37, s15, s27
	s_cselect_b32 s36, s30, s26
	v_add_u32_e32 v138, s43, v151
	s_cselect_b32 s27, s13, s73
	s_cselect_b32 s26, s31, s56
	s_add_i32 s61, 0, 0x14000
	ds_read_b128 v[146:149], v138
	ds_read_b128 v[156:159], v138 offset:1024
	ds_read_b128 v[160:163], v138 offset:2048
	ds_read_b128 v[164:167], v138 offset:3072
	v_add_u32_e32 v138, s61, v151
	ds_read_b128 v[168:171], v138
	ds_read_b128 v[172:175], v138 offset:1024
	ds_read_b128 v[176:179], v138 offset:2048
	ds_read_b128 v[180:183], v138 offset:3072
	v_lshl_add_u64 v[138:139], s[22:23], 0, v[134:135]
	s_add_i32 m0, s63, 0xc000
	ds_read_b128 v[184:187], v154
	ds_read_b128 v[188:191], v154 offset:1024
	ds_read_b128 v[192:195], v154 offset:2048
	ds_read_b128 v[196:199], v154 offset:3072
	ds_read_b128 v[208:211], v154 offset:4096
	ds_read_b128 v[212:215], v154 offset:5120
	ds_read_b128 v[216:219], v154 offset:6144
	ds_read_b128 v[220:223], v154 offset:7168
	global_load_lds_dwordx4 v[138:139], off
	v_lshl_add_u64 v[138:139], s[22:23], 0, v[136:137]
	s_add_i32 m0, s63, 0xe000
	s_nop 0
	global_load_lds_dwordx4 v[138:139], off
	v_lshl_add_u64 v[138:139], v[226:227], 0, s[84:85]
	s_mov_b32 m0, s70
	s_nop 0
	global_load_lds_dwordx4 v[138:139], off
	v_lshl_add_u64 v[138:139], v[228:229], 0, s[84:85]
	s_mov_b32 m0, s71
	s_nop 0
	global_load_lds_dwordx4 v[138:139], off
	s_waitcnt vmcnt(8)
	s_waitcnt lgkmcnt(0)
	s_barrier
	s_setprio 1
	s_waitcnt lgkmcnt(0)
	v_mfma_f32_16x16x32_bf16 v[124:127], v[146:149], v[184:187], v[124:127]
	v_mfma_f32_16x16x32_bf16 v[120:123], v[160:163], v[184:187], v[120:123]
	v_mfma_f32_16x16x32_bf16 v[108:111], v[146:149], v[192:195], v[108:111]
	v_mfma_f32_16x16x32_bf16 v[104:107], v[160:163], v[192:195], v[104:107]
	v_mfma_f32_16x16x32_bf16 v[92:95], v[146:149], v[208:211], v[92:95]
	v_mfma_f32_16x16x32_bf16 v[88:91], v[160:163], v[208:211], v[88:91]
	v_mfma_f32_16x16x32_bf16 v[76:79], v[146:149], v[216:219], v[76:79]
	v_mfma_f32_16x16x32_bf16 v[72:75], v[160:163], v[216:219], v[72:75]
	v_mfma_f32_16x16x32_bf16 v[124:127], v[156:159], v[188:191], v[124:127]
	v_mfma_f32_16x16x32_bf16 v[120:123], v[164:167], v[188:191], v[120:123]
	v_mfma_f32_16x16x32_bf16 v[108:111], v[156:159], v[196:199], v[108:111]
	v_mfma_f32_16x16x32_bf16 v[104:107], v[164:167], v[196:199], v[104:107]
	v_mfma_f32_16x16x32_bf16 v[92:95], v[156:159], v[212:215], v[92:95]
	v_mfma_f32_16x16x32_bf16 v[88:91], v[164:167], v[212:215], v[88:91]
	v_mfma_f32_16x16x32_bf16 v[76:79], v[156:159], v[220:223], v[76:79]
	v_mfma_f32_16x16x32_bf16 v[72:75], v[164:167], v[220:223], v[72:75]
	s_setprio 0
	s_setprio 1
	v_mfma_f32_16x16x32_bf16 v[116:119], v[168:171], v[184:187], v[116:119]
	v_mfma_f32_16x16x32_bf16 v[112:115], v[176:179], v[184:187], v[112:115]
	v_mfma_f32_16x16x32_bf16 v[100:103], v[168:171], v[192:195], v[100:103]
	v_mfma_f32_16x16x32_bf16 v[96:99], v[176:179], v[192:195], v[96:99]
	v_mfma_f32_16x16x32_bf16 v[84:87], v[168:171], v[208:211], v[84:87]
	v_mfma_f32_16x16x32_bf16 v[80:83], v[176:179], v[208:211], v[80:83]
	v_mfma_f32_16x16x32_bf16 v[68:71], v[168:171], v[216:219], v[68:71]
	v_mfma_f32_16x16x32_bf16 v[64:67], v[176:179], v[216:219], v[64:67]
	v_mfma_f32_16x16x32_bf16 v[116:119], v[172:175], v[188:191], v[116:119]
	v_mfma_f32_16x16x32_bf16 v[112:115], v[180:183], v[188:191], v[112:115]
	v_mfma_f32_16x16x32_bf16 v[100:103], v[172:175], v[196:199], v[100:103]
	v_mfma_f32_16x16x32_bf16 v[96:99], v[180:183], v[196:199], v[96:99]
	v_mfma_f32_16x16x32_bf16 v[84:87], v[172:175], v[212:215], v[84:87]
	v_mfma_f32_16x16x32_bf16 v[80:83], v[180:183], v[212:215], v[80:83]
	v_mfma_f32_16x16x32_bf16 v[68:71], v[172:175], v[220:223], v[68:71]
	v_mfma_f32_16x16x32_bf16 v[64:67], v[180:183], v[220:223], v[64:67]
	s_setprio 0
	s_barrier
	s_add_i32 s43, s43, s62
	v_lshl_add_u64 v[138:139], s[26:27], 0, v[140:141]
	s_mov_b32 m0, s43
	ds_read_b128 v[184:187], v154 offset:16384
	ds_read_b128 v[188:191], v154 offset:17408
	ds_read_b128 v[192:195], v154 offset:18432
	ds_read_b128 v[196:199], v154 offset:19456
	ds_read_b128 v[208:211], v154 offset:20480
	ds_read_b128 v[212:215], v154 offset:21504
	ds_read_b128 v[216:219], v154 offset:22528
	ds_read_b128 v[220:223], v154 offset:23552
	global_load_lds_dwordx4 v[138:139], off
	s_add_i32 m0, s43, 0x2000
	s_add_u32 s80, s26, 0x80000
	v_lshl_add_u64 v[224:225], s[26:27], 0, v[128:129]
	s_addc_u32 s81, s27, 0
	s_add_i32 s43, s61, s62
	global_load_lds_dwordx4 v[224:225], off
	v_lshl_add_u64 v[226:227], s[80:81], 0, v[140:141]
	s_mov_b32 m0, s43
	s_nop 0
	global_load_lds_dwordx4 v[226:227], off
	v_lshl_add_u64 v[226:227], s[80:81], 0, v[128:129]
	s_add_i32 m0, s43, 0x2000
	s_nop 0
	global_load_lds_dwordx4 v[226:227], off
	s_waitcnt vmcnt(4)
	s_waitcnt lgkmcnt(0)
	s_barrier
; #define PG8_STAGE(bufoff, gbase, voff) do { _Pragma("unroll") for (int _i = 0; _i < 2; ++_i) \
;         __builtin_amdgcn_global_load_lds((const unsigned*)((const char*)(gbase) + (voff)[_i]), (PG8_LAS unsigned*)(lds + (bufoff) + ldsw + _i * 8192), 16, 0, 0); } while (0)
; #define PG8_LDA(dst, b, h) do { _Pragma("unroll") for (int m = 0; m < 4; ++m) _Pragma("unroll") for (int k = 0; k < 2; ++k) dst[m][k] = *(const PG8_LAS bf16x8*)(lds + PG8_SA(b, h) + aoff + m * 2048 + k * 1024); } while (0)
; #define PG8_LDB(dst, b, h) do { _Pragma("unroll") for (int n = 0; n < 2; ++n) _Pragma("unroll") for (int k = 0; k < 2; ++k) dst[n][k] = *(const PG8_LAS bf16x8*)(lds + PG8_SB(b, h) + boff + n * 2048 + k * 1024); } while (0)
; #define PG8_MMA(ai, bj, At, Bt) do { __builtin_amdgcn_s_setprio(1); _Pragma("unroll") for (int m = 0; m < 4; ++m) _Pragma("unroll") for (int n = 0; n < 2; ++n) _Pragma("unroll") for (int k = 0; k < 2; ++k) \
;         acc[ai][bj][m][n] = __builtin_amdgcn_mfma_f32_16x16x32_bf16(Bt[n][k], At[m][k], acc[ai][bj][m][n], 0, 0, 0); __builtin_amdgcn_s_setprio(0); } while (0)
; #define PG8_WAIT_V(n) asm volatile("s_waitcnt vmcnt(" #n ")" ::: "memory")
; #define PG8_WAIT_L(n) asm volatile("s_waitcnt lgkmcnt(" #n ")" ::: "memory")
; #define PG8_BAR __builtin_amdgcn_s_barrier()
; #define PG8_SCHED __builtin_amdgcn_sched_barrier(0)
; template <class Epi, class Sched, bool ALIGN_EPI = false, bool SP2 = false>
; __device__ __forceinline__ void gemm_phase(PG8_LAS unsigned char* lds, const Gemm g, const Sched& S, const Epi& E) {
;     ...
;             PG8_WAIT_V(8); PG8_WAIT_L(0); PG8_BAR; PG8_MMA(1, 0, At, B0); PG8_MMA(1, 1, At, B1); PG8_BAR; PG8_SCHED;
;             PG8_LDB(B0, 1, 0); PG8_LDB(B1, 1, 1); PG8_SCHED; PG8_LDA(At, 1, 0); PG8_STAGE(PG8_SA(0, 1), a2 + hstep, voffA);
;             PG8_WAIT_V(8); PG8_WAIT_L(0); PG8_BAR; PG8_MMA(0, 0, At, B0); PG8_MMA(0, 1, At, B1); PG8_BAR; PG8_SCHED;
	s_setprio 1
	s_waitcnt lgkmcnt(0)
	v_mfma_f32_16x16x32_bf16 v[60:63], v[146:149], v[184:187], v[60:63]
	v_mfma_f32_16x16x32_bf16 v[56:59], v[160:163], v[184:187], v[56:59]
	v_mfma_f32_16x16x32_bf16 v[44:47], v[146:149], v[192:195], v[44:47]
	v_mfma_f32_16x16x32_bf16 v[40:43], v[160:163], v[192:195], v[40:43]
	v_mfma_f32_16x16x32_bf16 v[28:31], v[146:149], v[208:211], v[28:31]
	v_mfma_f32_16x16x32_bf16 v[24:27], v[160:163], v[208:211], v[24:27]
	v_mfma_f32_16x16x32_bf16 v[12:15], v[146:149], v[216:219], v[12:15]
	v_mfma_f32_16x16x32_bf16 v[8:11], v[160:163], v[216:219], v[8:11]
	v_mfma_f32_16x16x32_bf16 v[60:63], v[156:159], v[188:191], v[60:63]
	v_mfma_f32_16x16x32_bf16 v[56:59], v[164:167], v[188:191], v[56:59]
	v_mfma_f32_16x16x32_bf16 v[44:47], v[156:159], v[196:199], v[44:47]
	v_mfma_f32_16x16x32_bf16 v[40:43], v[164:167], v[196:199], v[40:43]
	v_mfma_f32_16x16x32_bf16 v[28:31], v[156:159], v[212:215], v[28:31]
	v_mfma_f32_16x16x32_bf16 v[24:27], v[164:167], v[212:215], v[24:27]
	v_mfma_f32_16x16x32_bf16 v[12:15], v[156:159], v[220:223], v[12:15]
	v_mfma_f32_16x16x32_bf16 v[8:11], v[164:167], v[220:223], v[8:11]
	s_setprio 0
	s_setprio 1
	v_mfma_f32_16x16x32_bf16 v[52:55], v[168:171], v[184:187], v[52:55]
	v_mfma_f32_16x16x32_bf16 v[48:51], v[176:179], v[184:187], v[48:51]
	v_mfma_f32_16x16x32_bf16 v[36:39], v[168:171], v[192:195], v[36:39]
	v_mfma_f32_16x16x32_bf16 v[32:35], v[176:179], v[192:195], v[32:35]
	v_mfma_f32_16x16x32_bf16 v[20:23], v[168:171], v[208:211], v[20:23]
	v_mfma_f32_16x16x32_bf16 v[16:19], v[176:179], v[208:211], v[16:19]
	v_mfma_f32_16x16x32_bf16 v[4:7], v[168:171], v[216:219], v[4:7]
	v_mfma_f32_16x16x32_bf16 v[0:3], v[176:179], v[216:219], v[0:3]
	v_mfma_f32_16x16x32_bf16 v[52:55], v[172:175], v[188:191], v[52:55]
	v_mfma_f32_16x16x32_bf16 v[48:51], v[180:183], v[188:191], v[48:51]
	v_mfma_f32_16x16x32_bf16 v[36:39], v[172:175], v[196:199], v[36:39]
	v_mfma_f32_16x16x32_bf16 v[32:35], v[180:183], v[196:199], v[32:35]
	v_mfma_f32_16x16x32_bf16 v[20:23], v[172:175], v[212:215], v[20:23]
	v_mfma_f32_16x16x32_bf16 v[16:19], v[180:183], v[212:215], v[16:19]
	v_mfma_f32_16x16x32_bf16 v[4:7], v[172:175], v[220:223], v[4:7]
	v_mfma_f32_16x16x32_bf16 v[0:3], v[180:183], v[220:223], v[0:3]
	s_setprio 0
	s_barrier
	s_add_i32 s43, 0, 0x18000
	v_add_u32_e32 v155, s43, v151
	s_add_i32 s61, 0, 0x1c000
	ds_read_b128 v[146:149], v155
	ds_read_b128 v[156:159], v155 offset:1024
	ds_read_b128 v[160:163], v155 offset:2048
	ds_read_b128 v[164:167], v155 offset:3072
	v_add_u32_e32 v155, s61, v151
	ds_read_b128 v[168:171], v155
	ds_read_b128 v[172:175], v155 offset:1024
	ds_read_b128 v[176:179], v155 offset:2048
	ds_read_b128 v[180:183], v155 offset:3072
	v_lshl_add_u64 v[226:227], s[36:37], 0, v[132:133]
	s_mov_b32 m0, s63
	s_nop 0
	global_load_lds_dwordx4 v[226:227], off
	v_lshl_add_u64 v[228:229], s[36:37], 0, v[130:131]
	s_mov_b32 m0, s64
	s_nop 0
	global_load_lds_dwordx4 v[228:229], off
	s_add_u32 s36, s36, 0x80000
	s_addc_u32 s37, s37, 0
	s_mov_b32 m0, s65
	v_lshl_add_u64 v[230:231], s[36:37], 0, v[132:133]
	ds_read_b128 v[184:187], v154 offset:32768
	ds_read_b128 v[188:191], v154 offset:33792
	ds_read_b128 v[192:195], v154 offset:34816
	ds_read_b128 v[196:199], v154 offset:35840
	ds_read_b128 v[208:211], v154 offset:36864
	ds_read_b128 v[212:215], v154 offset:37888
	ds_read_b128 v[216:219], v154 offset:38912
	ds_read_b128 v[220:223], v154 offset:39936
	global_load_lds_dwordx4 v[230:231], off
	v_lshl_add_u64 v[230:231], s[36:37], 0, v[130:131]
	s_mov_b32 m0, s67
	s_nop 0
	global_load_lds_dwordx4 v[230:231], off
	s_waitcnt vmcnt(8)
	s_waitcnt lgkmcnt(0)
	s_barrier
; #define PG8_STAGE(bufoff, gbase, voff) do { _Pragma("unroll") for (int _i = 0; _i < 2; ++_i) \
;         __builtin_amdgcn_global_load_lds((const unsigned*)((const char*)(gbase) + (voff)[_i]), (PG8_LAS unsigned*)(lds + (bufoff) + ldsw + _i * 8192), 16, 0, 0); } while (0)
; #define PG8_LDA(dst, b, h) do { _Pragma("unroll") for (int m = 0; m < 4; ++m) _Pragma("unroll") for (int k = 0; k < 2; ++k) dst[m][k] = *(const PG8_LAS bf16x8*)(lds + PG8_SA(b, h) + aoff + m * 2048 + k * 1024); } while (0)
; #define PG8_MMA(ai, bj, At, Bt) do { __builtin_amdgcn_s_setprio(1); _Pragma("unroll") for (int m = 0; m < 4; ++m) _Pragma("unroll") for (int n = 0; n < 2; ++n) _Pragma("unroll") for (int k = 0; k < 2; ++k) \
;         acc[ai][bj][m][n] = __builtin_amdgcn_mfma_f32_16x16x32_bf16(Bt[n][k], At[m][k], acc[ai][bj][m][n], 0, 0, 0); __builtin_amdgcn_s_setprio(0); } while (0)
; #define PG8_WAIT_V(n) asm volatile("s_waitcnt vmcnt(" #n ")" ::: "memory")
; #define PG8_WAIT_L(n) asm volatile("s_waitcnt lgkmcnt(" #n ")" ::: "memory")
; #define PG8_BAR __builtin_amdgcn_s_barrier()
; #define PG8_SCHED __builtin_amdgcn_sched_barrier(0)
; template <class Epi, class Sched, bool ALIGN_EPI = false, bool SP2 = false>
; __device__ __forceinline__ void gemm_phase(PG8_LAS unsigned char* lds, const Gemm g, const Sched& S, const Epi& E) {
;     ...
;         for (int t = 0; t < nt; t += 2) {
;     ...
;             PG8_WAIT_V(8); PG8_WAIT_L(0); PG8_BAR; PG8_MMA(0, 0, At, B0); PG8_MMA(0, 1, At, B1); PG8_BAR; PG8_SCHED;
;             PG8_LDA(At, 1, 1); PG8_STAGE(PG8_SB(1, 0), b3, voffB); PG8_STAGE(PG8_SB(1, 1), b3 + hstep, voffB); PG8_STAGE(PG8_SA(1, 0), a3, voffA);
;             PG8_WAIT_V(8); PG8_WAIT_L(0); PG8_BAR; PG8_MMA(1, 0, At, B0); PG8_MMA(1, 1, At, B1); PG8_BAR; PG8_SCHED;
	s_setprio 1
	s_waitcnt lgkmcnt(0)
	v_mfma_f32_16x16x32_bf16 v[124:127], v[146:149], v[184:187], v[124:127]
	v_mfma_f32_16x16x32_bf16 v[120:123], v[160:163], v[184:187], v[120:123]
	v_mfma_f32_16x16x32_bf16 v[108:111], v[146:149], v[192:195], v[108:111]
	v_mfma_f32_16x16x32_bf16 v[104:107], v[160:163], v[192:195], v[104:107]
	v_mfma_f32_16x16x32_bf16 v[92:95], v[146:149], v[208:211], v[92:95]
	v_mfma_f32_16x16x32_bf16 v[88:91], v[160:163], v[208:211], v[88:91]
	v_mfma_f32_16x16x32_bf16 v[76:79], v[146:149], v[216:219], v[76:79]
	v_mfma_f32_16x16x32_bf16 v[72:75], v[160:163], v[216:219], v[72:75]
	v_mfma_f32_16x16x32_bf16 v[124:127], v[156:159], v[188:191], v[124:127]
	v_mfma_f32_16x16x32_bf16 v[120:123], v[164:167], v[188:191], v[120:123]
	v_mfma_f32_16x16x32_bf16 v[108:111], v[156:159], v[196:199], v[108:111]
	v_mfma_f32_16x16x32_bf16 v[104:107], v[164:167], v[196:199], v[104:107]
	v_mfma_f32_16x16x32_bf16 v[92:95], v[156:159], v[212:215], v[92:95]
	v_mfma_f32_16x16x32_bf16 v[88:91], v[164:167], v[212:215], v[88:91]
	v_mfma_f32_16x16x32_bf16 v[76:79], v[156:159], v[220:223], v[76:79]
	v_mfma_f32_16x16x32_bf16 v[72:75], v[164:167], v[220:223], v[72:75]
	s_setprio 0
	s_setprio 1
	v_mfma_f32_16x16x32_bf16 v[116:119], v[168:171], v[184:187], v[116:119]
	v_mfma_f32_16x16x32_bf16 v[112:115], v[176:179], v[184:187], v[112:115]
	v_mfma_f32_16x16x32_bf16 v[100:103], v[168:171], v[192:195], v[100:103]
	v_mfma_f32_16x16x32_bf16 v[96:99], v[176:179], v[192:195], v[96:99]
	v_mfma_f32_16x16x32_bf16 v[84:87], v[168:171], v[208:211], v[84:87]
	v_mfma_f32_16x16x32_bf16 v[80:83], v[176:179], v[208:211], v[80:83]
	v_mfma_f32_16x16x32_bf16 v[68:71], v[168:171], v[216:219], v[68:71]
	v_mfma_f32_16x16x32_bf16 v[64:67], v[176:179], v[216:219], v[64:67]
	v_mfma_f32_16x16x32_bf16 v[116:119], v[172:175], v[188:191], v[116:119]
	v_mfma_f32_16x16x32_bf16 v[112:115], v[180:183], v[188:191], v[112:115]
	v_mfma_f32_16x16x32_bf16 v[100:103], v[172:175], v[196:199], v[100:103]
	v_mfma_f32_16x16x32_bf16 v[96:99], v[180:183], v[196:199], v[96:99]
	v_mfma_f32_16x16x32_bf16 v[84:87], v[172:175], v[212:215], v[84:87]
	v_mfma_f32_16x16x32_bf16 v[80:83], v[180:183], v[212:215], v[80:83]
	v_mfma_f32_16x16x32_bf16 v[68:71], v[172:175], v[220:223], v[68:71]
	v_mfma_f32_16x16x32_bf16 v[64:67], v[180:183], v[220:223], v[64:67]
	s_setprio 0
	s_barrier
	s_add_i32 s36, s43, s62
	v_lshl_add_u64 v[138:139], v[138:139], 0, s[84:85]
	s_mov_b32 m0, s36
	ds_read_b128 v[184:187], v154 offset:49152
	ds_read_b128 v[188:191], v154 offset:50176
	ds_read_b128 v[192:195], v154 offset:51200
	ds_read_b128 v[196:199], v154 offset:52224
	ds_read_b128 v[208:211], v154 offset:53248
	ds_read_b128 v[212:215], v154 offset:54272
	ds_read_b128 v[216:219], v154 offset:55296
	ds_read_b128 v[220:223], v154 offset:56320
	global_load_lds_dwordx4 v[138:139], off
	s_add_i32 m0, s36, 0x2000
	s_add_u32 s26, s26, 0x80080
	v_lshl_add_u64 v[138:139], v[224:225], 0, s[84:85]
	s_addc_u32 s27, s27, 0
	s_add_i32 s36, s61, s62
	global_load_lds_dwordx4 v[138:139], off
	v_lshl_add_u64 v[138:139], s[26:27], 0, v[140:141]
	s_mov_b32 m0, s36
	s_nop 0
	global_load_lds_dwordx4 v[138:139], off
	v_lshl_add_u64 v[138:139], s[26:27], 0, v[128:129]
	s_add_i32 m0, s36, 0x2000
	s_nop 0
	global_load_lds_dwordx4 v[138:139], off
	s_waitcnt vmcnt(4)
	s_waitcnt lgkmcnt(0)
	s_barrier
	s_setprio 1
	s_waitcnt lgkmcnt(0)
	v_mfma_f32_16x16x32_bf16 v[60:63], v[146:149], v[184:187], v[60:63]
	v_mfma_f32_16x16x32_bf16 v[56:59], v[160:163], v[184:187], v[56:59]
	v_mfma_f32_16x16x32_bf16 v[44:47], v[146:149], v[192:195], v[44:47]
	v_mfma_f32_16x16x32_bf16 v[40:43], v[160:163], v[192:195], v[40:43]
	v_mfma_f32_16x16x32_bf16 v[28:31], v[146:149], v[208:211], v[28:31]
	v_mfma_f32_16x16x32_bf16 v[24:27], v[160:163], v[208:211], v[24:27]
	v_mfma_f32_16x16x32_bf16 v[12:15], v[146:149], v[216:219], v[12:15]
	v_mfma_f32_16x16x32_bf16 v[8:11], v[160:163], v[216:219], v[8:11]
	v_mfma_f32_16x16x32_bf16 v[60:63], v[156:159], v[188:191], v[60:63]
	v_mfma_f32_16x16x32_bf16 v[56:59], v[164:167], v[188:191], v[56:59]
	v_mfma_f32_16x16x32_bf16 v[44:47], v[156:159], v[196:199], v[44:47]
	v_mfma_f32_16x16x32_bf16 v[40:43], v[164:167], v[196:199], v[40:43]
	v_mfma_f32_16x16x32_bf16 v[28:31], v[156:159], v[212:215], v[28:31]
	v_mfma_f32_16x16x32_bf16 v[24:27], v[164:167], v[212:215], v[24:27]
	v_mfma_f32_16x16x32_bf16 v[12:15], v[156:159], v[220:223], v[12:15]
	v_mfma_f32_16x16x32_bf16 v[8:11], v[164:167], v[220:223], v[8:11]
	s_setprio 0
	s_setprio 1
	v_mfma_f32_16x16x32_bf16 v[52:55], v[168:171], v[184:187], v[52:55]
	v_mfma_f32_16x16x32_bf16 v[48:51], v[176:179], v[184:187], v[48:51]
	v_mfma_f32_16x16x32_bf16 v[36:39], v[168:171], v[192:195], v[36:39]
	v_mfma_f32_16x16x32_bf16 v[32:35], v[176:179], v[192:195], v[32:35]
	v_mfma_f32_16x16x32_bf16 v[20:23], v[168:171], v[208:211], v[20:23]
	v_mfma_f32_16x16x32_bf16 v[16:19], v[176:179], v[208:211], v[16:19]
	v_mfma_f32_16x16x32_bf16 v[4:7], v[168:171], v[216:219], v[4:7]
	v_mfma_f32_16x16x32_bf16 v[0:3], v[176:179], v[216:219], v[0:3]
	v_mfma_f32_16x16x32_bf16 v[52:55], v[172:175], v[188:191], v[52:55]
	v_mfma_f32_16x16x32_bf16 v[48:51], v[180:183], v[188:191], v[48:51]
	v_mfma_f32_16x16x32_bf16 v[36:39], v[172:175], v[196:199], v[36:39]
	v_mfma_f32_16x16x32_bf16 v[32:35], v[180:183], v[196:199], v[32:35]
	v_mfma_f32_16x16x32_bf16 v[20:23], v[172:175], v[212:215], v[20:23]
	v_mfma_f32_16x16x32_bf16 v[16:19], v[180:183], v[212:215], v[16:19]
	v_mfma_f32_16x16x32_bf16 v[4:7], v[172:175], v[220:223], v[4:7]
	v_mfma_f32_16x16x32_bf16 v[0:3], v[180:183], v[220:223], v[0:3]
	s_setprio 0
	s_barrier
	s_add_i32 s76, s76, 2
	s_add_u32 s22, s22, 0x100
	s_addc_u32 s23, s23, 0
	s_add_u32 s56, s56, 0x100
	s_addc_u32 s73, s73, 0
	s_cmp_gt_u32 s76, 29
	s_cbranch_scc0 .LBB0_1010
	s_and_b64 vcc, exec, s[10:11]
	s_cbranch_vccz .LBB0_1013
	s_barrier

; #define PG8_STAGE(bufoff, gbase, voff) do { _Pragma("unroll") for (int _i = 0; _i < 2; ++_i) \
;         __builtin_amdgcn_global_load_lds((const unsigned*)((const char*)(gbase) + (voff)[_i]), (PG8_LAS unsigned*)(lds + (bufoff) + ldsw + _i * 8192), 16, 0, 0); } while (0)
; #define PG8_LDA(dst, b, h) do { _Pragma("unroll") for (int m = 0; m < 4; ++m) _Pragma("unroll") for (int k = 0; k < 2; ++k) dst[m][k] = *(const PG8_LAS bf16x8*)(lds + PG8_SA(b, h) + aoff + m * 2048 + k * 1024); } while (0)
; #define PG8_LDB(dst, b, h) do { _Pragma("unroll") for (int n = 0; n < 2; ++n) _Pragma("unroll") for (int k = 0; k < 2; ++k) dst[n][k] = *(const PG8_LAS bf16x8*)(lds + PG8_SB(b, h) + boff + n * 2048 + k * 1024); } while (0)
; #define PG8_MMA(ai, bj, At, Bt) do { __builtin_amdgcn_s_setprio(1); _Pragma("unroll") for (int m = 0; m < 4; ++m) _Pragma("unroll") for (int n = 0; n < 2; ++n) _Pragma("unroll") for (int k = 0; k < 2; ++k) \
;         acc[ai][bj][m][n] = __builtin_amdgcn_mfma_f32_16x16x32_bf16(Bt[n][k], At[m][k], acc[ai][bj][m][n], 0, 0, 0); __builtin_amdgcn_s_setprio(0); } while (0)
; #define PG8_WAIT_V(n) asm volatile("s_waitcnt vmcnt(" #n ")" ::: "memory")
; #define PG8_WAIT_L(n) asm volatile("s_waitcnt lgkmcnt(" #n ")" ::: "memory")
; #define PG8_BAR __builtin_amdgcn_s_barrier()
; #define PG8_SCHED __builtin_amdgcn_sched_barrier(0)
; template <class Epi, class Sched, bool ALIGN_EPI = false, bool SP2 = false>
; __device__ __forceinline__ void gemm_phase(PG8_LAS unsigned char* lds, const Gemm g, const Sched& S, const Epi& E) {
;     ...
;             PG8_LDB(B0, 0, 0); PG8_LDB(B1, 0, 1); PG8_SCHED; PG8_LDA(At, 0, 0); PG8_STAGE(PG8_SA(1, 1), a1 + hstep, voffA);
;             PG8_WAIT_V(8); PG8_WAIT_L(0); PG8_BAR; PG8_MMA(0, 0, At, B0); PG8_MMA(0, 1, At, B1); PG8_BAR; PG8_SCHED;
;             PG8_LDA(At, 0, 1); PG8_STAGE(PG8_SB(0, 0), b2, voffB); PG8_STAGE(PG8_SB(0, 1), b2 + hstep, voffB); PG8_STAGE(PG8_SA(0, 0), a2, voffA);
;             PG8_WAIT_V(8); PG8_WAIT_L(0); PG8_BAR; PG8_MMA(1, 0, At, B0); PG8_MMA(1, 1, At, B1); PG8_BAR; PG8_SCHED;
.LBB0_1146:
	s_add_u32 s54, s48, 0x100
	s_addc_u32 s55, s49, 0
	s_add_i32 s43, 0, 0x10000
	s_cmpk_eq_i32 s96, 0x7c
	s_cselect_b32 s65, s23, s55
	s_cselect_b32 s64, s30, s54
	v_add_u32_e32 v140, s43, v151
	s_cselect_b32 s63, s19, s95
	s_cselect_b32 s62, s31, s56
	s_add_i32 s61, 0, 0x14000
	ds_read_b128 v[136:139], v140
	ds_read_b128 v[146:149], v140 offset:1024
	ds_read_b128 v[154:157], v140 offset:2048
	ds_read_b128 v[160:163], v140 offset:3072
	v_add_u32_e32 v140, s61, v151
	ds_read_b128 v[164:167], v140
	ds_read_b128 v[168:171], v140 offset:1024
	ds_read_b128 v[172:175], v140 offset:2048
	ds_read_b128 v[176:179], v140 offset:3072
	v_lshl_add_u64 v[220:221], s[48:49], 0, v[132:133]
	s_add_i32 m0, s73, 0xc000
	ds_read_b128 v[180:183], v158
	ds_read_b128 v[184:187], v158 offset:1024
	ds_read_b128 v[188:191], v158 offset:2048
	ds_read_b128 v[192:195], v158 offset:3072
	ds_read_b128 v[196:199], v158 offset:4096
	ds_read_b128 v[208:211], v158 offset:5120
	ds_read_b128 v[212:215], v158 offset:6144
	ds_read_b128 v[216:219], v158 offset:7168
	global_load_lds_dwordx4 v[220:221], off
	v_lshl_add_u64 v[220:221], s[48:49], 0, v[134:135]
	s_add_i32 m0, s73, 0xe000
	s_nop 0
	global_load_lds_dwordx4 v[220:221], off
	v_lshl_add_u64 v[220:221], v[224:225], 0, s[84:85]
	s_mov_b32 m0, s92
	s_nop 0
	global_load_lds_dwordx4 v[220:221], off
	v_lshl_add_u64 v[220:221], v[226:227], 0, s[84:85]
	s_mov_b32 m0, s93
	s_nop 0
	global_load_lds_dwordx4 v[220:221], off
	s_waitcnt vmcnt(8)
	s_waitcnt lgkmcnt(0)
	s_barrier
	s_setprio 1
	s_waitcnt lgkmcnt(0)
	v_mfma_f32_16x16x32_bf16 v[124:127], v[136:139], v[180:183], v[124:127]
	v_mfma_f32_16x16x32_bf16 v[120:123], v[154:157], v[180:183], v[120:123]
	v_mfma_f32_16x16x32_bf16 v[108:111], v[136:139], v[188:191], v[108:111]
	v_mfma_f32_16x16x32_bf16 v[104:107], v[154:157], v[188:191], v[104:107]
	v_mfma_f32_16x16x32_bf16 v[92:95], v[136:139], v[196:199], v[92:95]
	v_mfma_f32_16x16x32_bf16 v[88:91], v[154:157], v[196:199], v[88:91]
	v_mfma_f32_16x16x32_bf16 v[76:79], v[136:139], v[212:215], v[76:79]
	v_mfma_f32_16x16x32_bf16 v[72:75], v[154:157], v[212:215], v[72:75]
	v_mfma_f32_16x16x32_bf16 v[124:127], v[146:149], v[184:187], v[124:127]
	v_mfma_f32_16x16x32_bf16 v[120:123], v[160:163], v[184:187], v[120:123]
	v_mfma_f32_16x16x32_bf16 v[108:111], v[146:149], v[192:195], v[108:111]
	v_mfma_f32_16x16x32_bf16 v[104:107], v[160:163], v[192:195], v[104:107]
	v_mfma_f32_16x16x32_bf16 v[92:95], v[146:149], v[208:211], v[92:95]
	v_mfma_f32_16x16x32_bf16 v[88:91], v[160:163], v[208:211], v[88:91]
	v_mfma_f32_16x16x32_bf16 v[76:79], v[146:149], v[216:219], v[76:79]
	v_mfma_f32_16x16x32_bf16 v[72:75], v[160:163], v[216:219], v[72:75]
	s_setprio 0
	s_setprio 1
	v_mfma_f32_16x16x32_bf16 v[116:119], v[164:167], v[180:183], v[116:119]
	v_mfma_f32_16x16x32_bf16 v[112:115], v[172:175], v[180:183], v[112:115]
	v_mfma_f32_16x16x32_bf16 v[100:103], v[164:167], v[188:191], v[100:103]
	v_mfma_f32_16x16x32_bf16 v[96:99], v[172:175], v[188:191], v[96:99]
	v_mfma_f32_16x16x32_bf16 v[84:87], v[164:167], v[196:199], v[84:87]
	v_mfma_f32_16x16x32_bf16 v[80:83], v[172:175], v[196:199], v[80:83]
	v_mfma_f32_16x16x32_bf16 v[68:71], v[164:167], v[212:215], v[68:71]
	v_mfma_f32_16x16x32_bf16 v[64:67], v[172:175], v[212:215], v[64:67]
	v_mfma_f32_16x16x32_bf16 v[116:119], v[168:171], v[184:187], v[116:119]
	v_mfma_f32_16x16x32_bf16 v[112:115], v[176:179], v[184:187], v[112:115]
	v_mfma_f32_16x16x32_bf16 v[100:103], v[168:171], v[192:195], v[100:103]
	v_mfma_f32_16x16x32_bf16 v[96:99], v[176:179], v[192:195], v[96:99]
	v_mfma_f32_16x16x32_bf16 v[84:87], v[168:171], v[208:211], v[84:87]
	v_mfma_f32_16x16x32_bf16 v[80:83], v[176:179], v[208:211], v[80:83]
	v_mfma_f32_16x16x32_bf16 v[68:71], v[168:171], v[216:219], v[68:71]
	v_mfma_f32_16x16x32_bf16 v[64:67], v[176:179], v[216:219], v[64:67]
	s_setprio 0
	s_barrier
	s_add_i32 s43, s43, s72
	v_lshl_add_u64 v[220:221], s[62:63], 0, v[130:131]
	s_mov_b32 m0, s43
	ds_read_b128 v[180:183], v158 offset:16384
	ds_read_b128 v[184:187], v158 offset:17408
	ds_read_b128 v[188:191], v158 offset:18432
	ds_read_b128 v[192:195], v158 offset:19456
	ds_read_b128 v[196:199], v158 offset:20480
	ds_read_b128 v[208:211], v158 offset:21504
	ds_read_b128 v[212:215], v158 offset:22528
	ds_read_b128 v[216:219], v158 offset:23552
	global_load_lds_dwordx4 v[220:221], off
	s_add_i32 m0, s43, 0x2000
	s_add_u32 s48, s62, 0x200000
	v_lshl_add_u64 v[222:223], s[62:63], 0, v[128:129]
	s_addc_u32 s49, s63, 0
	s_add_i32 s43, s61, s72
	global_load_lds_dwordx4 v[222:223], off
	v_lshl_add_u64 v[224:225], s[48:49], 0, v[130:131]
	s_mov_b32 m0, s43
	s_nop 0
	global_load_lds_dwordx4 v[224:225], off
	v_lshl_add_u64 v[224:225], s[48:49], 0, v[128:129]
	s_add_i32 m0, s43, 0x2000
	s_nop 0
	global_load_lds_dwordx4 v[224:225], off
	s_waitcnt vmcnt(4)
	s_waitcnt lgkmcnt(0)
	s_barrier
; #define PG8_STAGE(bufoff, gbase, voff) do { _Pragma("unroll") for (int _i = 0; _i < 2; ++_i) \
;         __builtin_amdgcn_global_load_lds((const unsigned*)((const char*)(gbase) + (voff)[_i]), (PG8_LAS unsigned*)(lds + (bufoff) + ldsw + _i * 8192), 16, 0, 0); } while (0)
; #define PG8_LDA(dst, b, h) do { _Pragma("unroll") for (int m = 0; m < 4; ++m) _Pragma("unroll") for (int k = 0; k < 2; ++k) dst[m][k] = *(const PG8_LAS bf16x8*)(lds + PG8_SA(b, h) + aoff + m * 2048 + k * 1024); } while (0)
; #define PG8_LDB(dst, b, h) do { _Pragma("unroll") for (int n = 0; n < 2; ++n) _Pragma("unroll") for (int k = 0; k < 2; ++k) dst[n][k] = *(const PG8_LAS bf16x8*)(lds + PG8_SB(b, h) + boff + n * 2048 + k * 1024); } while (0)
; #define PG8_MMA(ai, bj, At, Bt) do { __builtin_amdgcn_s_setprio(1); _Pragma("unroll") for (int m = 0; m < 4; ++m) _Pragma("unroll") for (int n = 0; n < 2; ++n) _Pragma("unroll") for (int k = 0; k < 2; ++k) \
;         acc[ai][bj][m][n] = __builtin_amdgcn_mfma_f32_16x16x32_bf16(Bt[n][k], At[m][k], acc[ai][bj][m][n], 0, 0, 0); __builtin_amdgcn_s_setprio(0); } while (0)
; #define PG8_WAIT_V(n) asm volatile("s_waitcnt vmcnt(" #n ")" ::: "memory")
; #define PG8_WAIT_L(n) asm volatile("s_waitcnt lgkmcnt(" #n ")" ::: "memory")
; #define PG8_BAR __builtin_amdgcn_s_barrier()
; #define PG8_SCHED __builtin_amdgcn_sched_barrier(0)
; template <class Epi, class Sched, bool ALIGN_EPI = false, bool SP2 = false>
; __device__ __forceinline__ void gemm_phase(PG8_LAS unsigned char* lds, const Gemm g, const Sched& S, const Epi& E) {
;     ...
;             PG8_WAIT_V(8); PG8_WAIT_L(0); PG8_BAR; PG8_MMA(1, 0, At, B0); PG8_MMA(1, 1, At, B1); PG8_BAR; PG8_SCHED;
;             PG8_LDB(B0, 1, 0); PG8_LDB(B1, 1, 1); PG8_SCHED; PG8_LDA(At, 1, 0); PG8_STAGE(PG8_SA(0, 1), a2 + hstep, voffA);
;             PG8_WAIT_V(8); PG8_WAIT_L(0); PG8_BAR; PG8_MMA(0, 0, At, B0); PG8_MMA(0, 1, At, B1); PG8_BAR; PG8_SCHED;
	s_setprio 1
	s_waitcnt lgkmcnt(0)
	v_mfma_f32_16x16x32_bf16 v[60:63], v[136:139], v[180:183], v[60:63]
	v_mfma_f32_16x16x32_bf16 v[56:59], v[154:157], v[180:183], v[56:59]
	v_mfma_f32_16x16x32_bf16 v[44:47], v[136:139], v[188:191], v[44:47]
	v_mfma_f32_16x16x32_bf16 v[40:43], v[154:157], v[188:191], v[40:43]
	v_mfma_f32_16x16x32_bf16 v[28:31], v[136:139], v[196:199], v[28:31]
	v_mfma_f32_16x16x32_bf16 v[24:27], v[154:157], v[196:199], v[24:27]
	v_mfma_f32_16x16x32_bf16 v[12:15], v[136:139], v[212:215], v[12:15]
	v_mfma_f32_16x16x32_bf16 v[8:11], v[154:157], v[212:215], v[8:11]
	v_mfma_f32_16x16x32_bf16 v[60:63], v[146:149], v[184:187], v[60:63]
	v_mfma_f32_16x16x32_bf16 v[56:59], v[160:163], v[184:187], v[56:59]
	v_mfma_f32_16x16x32_bf16 v[44:47], v[146:149], v[192:195], v[44:47]
	v_mfma_f32_16x16x32_bf16 v[40:43], v[160:163], v[192:195], v[40:43]
	v_mfma_f32_16x16x32_bf16 v[28:31], v[146:149], v[208:211], v[28:31]
	v_mfma_f32_16x16x32_bf16 v[24:27], v[160:163], v[208:211], v[24:27]
	v_mfma_f32_16x16x32_bf16 v[12:15], v[146:149], v[216:219], v[12:15]
	v_mfma_f32_16x16x32_bf16 v[8:11], v[160:163], v[216:219], v[8:11]
	s_setprio 0
	s_setprio 1
	v_mfma_f32_16x16x32_bf16 v[52:55], v[164:167], v[180:183], v[52:55]
	v_mfma_f32_16x16x32_bf16 v[48:51], v[172:175], v[180:183], v[48:51]
	v_mfma_f32_16x16x32_bf16 v[36:39], v[164:167], v[188:191], v[36:39]
	v_mfma_f32_16x16x32_bf16 v[32:35], v[172:175], v[188:191], v[32:35]
	v_mfma_f32_16x16x32_bf16 v[20:23], v[164:167], v[196:199], v[20:23]
	v_mfma_f32_16x16x32_bf16 v[16:19], v[172:175], v[196:199], v[16:19]
	v_mfma_f32_16x16x32_bf16 v[4:7], v[164:167], v[212:215], v[4:7]
	v_mfma_f32_16x16x32_bf16 v[0:3], v[172:175], v[212:215], v[0:3]
	v_mfma_f32_16x16x32_bf16 v[52:55], v[168:171], v[184:187], v[52:55]
	v_mfma_f32_16x16x32_bf16 v[48:51], v[176:179], v[184:187], v[48:51]
	v_mfma_f32_16x16x32_bf16 v[36:39], v[168:171], v[192:195], v[36:39]
	v_mfma_f32_16x16x32_bf16 v[32:35], v[176:179], v[192:195], v[32:35]
	v_mfma_f32_16x16x32_bf16 v[20:23], v[168:171], v[208:211], v[20:23]
	v_mfma_f32_16x16x32_bf16 v[16:19], v[176:179], v[208:211], v[16:19]
	v_mfma_f32_16x16x32_bf16 v[4:7], v[168:171], v[216:219], v[4:7]
	v_mfma_f32_16x16x32_bf16 v[0:3], v[176:179], v[216:219], v[0:3]
	s_setprio 0
	s_barrier
	s_add_i32 s43, 0, 0x18000
	v_add_u32_e32 v140, s43, v151
	s_add_i32 s61, 0, 0x1c000
	ds_read_b128 v[136:139], v140
	ds_read_b128 v[146:149], v140 offset:1024
	ds_read_b128 v[154:157], v140 offset:2048
	ds_read_b128 v[160:163], v140 offset:3072
	v_add_u32_e32 v140, s61, v151
	ds_read_b128 v[164:167], v140
	ds_read_b128 v[168:171], v140 offset:1024
	ds_read_b128 v[172:175], v140 offset:2048
	ds_read_b128 v[176:179], v140 offset:3072
	v_lshl_add_u64 v[224:225], s[64:65], 0, v[130:131]
	s_mov_b32 m0, s73
	s_nop 0
	global_load_lds_dwordx4 v[224:225], off
	v_lshl_add_u64 v[226:227], s[64:65], 0, v[128:129]
	s_mov_b32 m0, s76
	s_nop 0
	global_load_lds_dwordx4 v[226:227], off
	s_add_u32 s48, s64, 0x200000
	s_addc_u32 s49, s65, 0
	s_mov_b32 m0, s90
	v_lshl_add_u64 v[228:229], s[48:49], 0, v[130:131]
	ds_read_b128 v[180:183], v158 offset:32768
	ds_read_b128 v[184:187], v158 offset:33792
	ds_read_b128 v[188:191], v158 offset:34816
	ds_read_b128 v[192:195], v158 offset:35840
	ds_read_b128 v[196:199], v158 offset:36864
	ds_read_b128 v[208:211], v158 offset:37888
	ds_read_b128 v[212:215], v158 offset:38912
	ds_read_b128 v[216:219], v158 offset:39936
	global_load_lds_dwordx4 v[228:229], off
	v_lshl_add_u64 v[228:229], s[48:49], 0, v[128:129]
	s_mov_b32 m0, s91
	s_nop 0
	global_load_lds_dwordx4 v[228:229], off
	s_waitcnt vmcnt(8)
	s_waitcnt lgkmcnt(0)
	s_barrier
; #define PG8_STAGE(bufoff, gbase, voff) do { _Pragma("unroll") for (int _i = 0; _i < 2; ++_i) \
;         __builtin_amdgcn_global_load_lds((const unsigned*)((const char*)(gbase) + (voff)[_i]), (PG8_LAS unsigned*)(lds + (bufoff) + ldsw + _i * 8192), 16, 0, 0); } while (0)
; #define PG8_LDA(dst, b, h) do { _Pragma("unroll") for (int m = 0; m < 4; ++m) _Pragma("unroll") for (int k = 0; k < 2; ++k) dst[m][k] = *(const PG8_LAS bf16x8*)(lds + PG8_SA(b, h) + aoff + m * 2048 + k * 1024); } while (0)
; #define PG8_MMA(ai, bj, At, Bt) do { __builtin_amdgcn_s_setprio(1); _Pragma("unroll") for (int m = 0; m < 4; ++m) _Pragma("unroll") for (int n = 0; n < 2; ++n) _Pragma("unroll") for (int k = 0; k < 2; ++k) \
;         acc[ai][bj][m][n] = __builtin_amdgcn_mfma_f32_16x16x32_bf16(Bt[n][k], At[m][k], acc[ai][bj][m][n], 0, 0, 0); __builtin_amdgcn_s_setprio(0); } while (0)
; #define PG8_WAIT_V(n) asm volatile("s_waitcnt vmcnt(" #n ")" ::: "memory")
; #define PG8_WAIT_L(n) asm volatile("s_waitcnt lgkmcnt(" #n ")" ::: "memory")
; #define PG8_BAR __builtin_amdgcn_s_barrier()
; #define PG8_SCHED __builtin_amdgcn_sched_barrier(0)
; template <class Epi, class Sched, bool ALIGN_EPI = false, bool SP2 = false>
; __device__ __forceinline__ void gemm_phase(PG8_LAS unsigned char* lds, const Gemm g, const Sched& S, const Epi& E) {
;     ...
;         for (int t = 0; t < nt; t += 2) {
;     ...
;             PG8_WAIT_V(8); PG8_WAIT_L(0); PG8_BAR; PG8_MMA(0, 0, At, B0); PG8_MMA(0, 1, At, B1); PG8_BAR; PG8_SCHED;
;             PG8_LDA(At, 1, 1); PG8_STAGE(PG8_SB(1, 0), b3, voffB); PG8_STAGE(PG8_SB(1, 1), b3 + hstep, voffB); PG8_STAGE(PG8_SA(1, 0), a3, voffA);
;             PG8_WAIT_V(8); PG8_WAIT_L(0); PG8_BAR; PG8_MMA(1, 0, At, B0); PG8_MMA(1, 1, At, B1); PG8_BAR; PG8_SCHED;
	s_setprio 1
	s_waitcnt lgkmcnt(0)
	v_mfma_f32_16x16x32_bf16 v[124:127], v[136:139], v[180:183], v[124:127]
	v_mfma_f32_16x16x32_bf16 v[120:123], v[154:157], v[180:183], v[120:123]
	v_mfma_f32_16x16x32_bf16 v[108:111], v[136:139], v[188:191], v[108:111]
	v_mfma_f32_16x16x32_bf16 v[104:107], v[154:157], v[188:191], v[104:107]
	v_mfma_f32_16x16x32_bf16 v[92:95], v[136:139], v[196:199], v[92:95]
	v_mfma_f32_16x16x32_bf16 v[88:91], v[154:157], v[196:199], v[88:91]
	v_mfma_f32_16x16x32_bf16 v[76:79], v[136:139], v[212:215], v[76:79]
	v_mfma_f32_16x16x32_bf16 v[72:75], v[154:157], v[212:215], v[72:75]
	v_mfma_f32_16x16x32_bf16 v[124:127], v[146:149], v[184:187], v[124:127]
	v_mfma_f32_16x16x32_bf16 v[120:123], v[160:163], v[184:187], v[120:123]
	v_mfma_f32_16x16x32_bf16 v[108:111], v[146:149], v[192:195], v[108:111]
	v_mfma_f32_16x16x32_bf16 v[104:107], v[160:163], v[192:195], v[104:107]
	v_mfma_f32_16x16x32_bf16 v[92:95], v[146:149], v[208:211], v[92:95]
	v_mfma_f32_16x16x32_bf16 v[88:91], v[160:163], v[208:211], v[88:91]
	v_mfma_f32_16x16x32_bf16 v[76:79], v[146:149], v[216:219], v[76:79]
	v_mfma_f32_16x16x32_bf16 v[72:75], v[160:163], v[216:219], v[72:75]
	s_setprio 0
	s_setprio 1
	v_mfma_f32_16x16x32_bf16 v[116:119], v[164:167], v[180:183], v[116:119]
	v_mfma_f32_16x16x32_bf16 v[112:115], v[172:175], v[180:183], v[112:115]
	v_mfma_f32_16x16x32_bf16 v[100:103], v[164:167], v[188:191], v[100:103]
	v_mfma_f32_16x16x32_bf16 v[96:99], v[172:175], v[188:191], v[96:99]
	v_mfma_f32_16x16x32_bf16 v[84:87], v[164:167], v[196:199], v[84:87]
	v_mfma_f32_16x16x32_bf16 v[80:83], v[172:175], v[196:199], v[80:83]
	v_mfma_f32_16x16x32_bf16 v[68:71], v[164:167], v[212:215], v[68:71]
	v_mfma_f32_16x16x32_bf16 v[64:67], v[172:175], v[212:215], v[64:67]
	v_mfma_f32_16x16x32_bf16 v[116:119], v[168:171], v[184:187], v[116:119]
	v_mfma_f32_16x16x32_bf16 v[112:115], v[176:179], v[184:187], v[112:115]
	v_mfma_f32_16x16x32_bf16 v[100:103], v[168:171], v[192:195], v[100:103]
	v_mfma_f32_16x16x32_bf16 v[96:99], v[176:179], v[192:195], v[96:99]
	v_mfma_f32_16x16x32_bf16 v[84:87], v[168:171], v[208:211], v[84:87]
	v_mfma_f32_16x16x32_bf16 v[80:83], v[176:179], v[208:211], v[80:83]
	v_mfma_f32_16x16x32_bf16 v[68:71], v[168:171], v[216:219], v[68:71]
	v_mfma_f32_16x16x32_bf16 v[64:67], v[176:179], v[216:219], v[64:67]
	s_setprio 0
	s_barrier
	s_add_i32 s43, s43, s72
	v_lshl_add_u64 v[220:221], v[220:221], 0, s[84:85]
	s_mov_b32 m0, s43
	ds_read_b128 v[180:183], v158 offset:49152
	ds_read_b128 v[184:187], v158 offset:50176
	ds_read_b128 v[188:191], v158 offset:51200
	ds_read_b128 v[192:195], v158 offset:52224
	ds_read_b128 v[196:199], v158 offset:53248
	ds_read_b128 v[208:211], v158 offset:54272
	ds_read_b128 v[212:215], v158 offset:55296
	ds_read_b128 v[216:219], v158 offset:56320
	global_load_lds_dwordx4 v[220:221], off
	s_add_i32 m0, s43, 0x2000
	s_add_u32 s48, s62, 0x200080
	v_lshl_add_u64 v[220:221], v[222:223], 0, s[84:85]
	s_addc_u32 s49, s63, 0
	s_add_i32 s43, s61, s72
	global_load_lds_dwordx4 v[220:221], off
	v_lshl_add_u64 v[220:221], s[48:49], 0, v[130:131]
	s_mov_b32 m0, s43
	s_nop 0
	global_load_lds_dwordx4 v[220:221], off
	v_lshl_add_u64 v[220:221], s[48:49], 0, v[128:129]
	s_add_i32 m0, s43, 0x2000
	s_nop 0
	global_load_lds_dwordx4 v[220:221], off
	s_waitcnt vmcnt(4)
	s_waitcnt lgkmcnt(0)
	s_barrier
	s_setprio 1
	s_waitcnt lgkmcnt(0)
	v_mfma_f32_16x16x32_bf16 v[60:63], v[136:139], v[180:183], v[60:63]
	v_mfma_f32_16x16x32_bf16 v[56:59], v[154:157], v[180:183], v[56:59]
	v_mfma_f32_16x16x32_bf16 v[44:47], v[136:139], v[188:191], v[44:47]
	v_mfma_f32_16x16x32_bf16 v[40:43], v[154:157], v[188:191], v[40:43]
	v_mfma_f32_16x16x32_bf16 v[28:31], v[136:139], v[196:199], v[28:31]
	v_mfma_f32_16x16x32_bf16 v[24:27], v[154:157], v[196:199], v[24:27]
	v_mfma_f32_16x16x32_bf16 v[12:15], v[136:139], v[212:215], v[12:15]
	v_mfma_f32_16x16x32_bf16 v[8:11], v[154:157], v[212:215], v[8:11]
	v_mfma_f32_16x16x32_bf16 v[60:63], v[146:149], v[184:187], v[60:63]
	v_mfma_f32_16x16x32_bf16 v[56:59], v[160:163], v[184:187], v[56:59]
	v_mfma_f32_16x16x32_bf16 v[44:47], v[146:149], v[192:195], v[44:47]
	v_mfma_f32_16x16x32_bf16 v[40:43], v[160:163], v[192:195], v[40:43]
	v_mfma_f32_16x16x32_bf16 v[28:31], v[146:149], v[208:211], v[28:31]
	v_mfma_f32_16x16x32_bf16 v[24:27], v[160:163], v[208:211], v[24:27]
	v_mfma_f32_16x16x32_bf16 v[12:15], v[146:149], v[216:219], v[12:15]
	v_mfma_f32_16x16x32_bf16 v[8:11], v[160:163], v[216:219], v[8:11]
	s_setprio 0
	s_setprio 1
	v_mfma_f32_16x16x32_bf16 v[52:55], v[164:167], v[180:183], v[52:55]
	v_mfma_f32_16x16x32_bf16 v[48:51], v[172:175], v[180:183], v[48:51]
	v_mfma_f32_16x16x32_bf16 v[36:39], v[164:167], v[188:191], v[36:39]
	v_mfma_f32_16x16x32_bf16 v[32:35], v[172:175], v[188:191], v[32:35]
	v_mfma_f32_16x16x32_bf16 v[20:23], v[164:167], v[196:199], v[20:23]
	v_mfma_f32_16x16x32_bf16 v[16:19], v[172:175], v[196:199], v[16:19]
	v_mfma_f32_16x16x32_bf16 v[4:7], v[164:167], v[212:215], v[4:7]
	v_mfma_f32_16x16x32_bf16 v[0:3], v[172:175], v[212:215], v[0:3]
	v_mfma_f32_16x16x32_bf16 v[52:55], v[168:171], v[184:187], v[52:55]
	v_mfma_f32_16x16x32_bf16 v[48:51], v[176:179], v[184:187], v[48:51]
	v_mfma_f32_16x16x32_bf16 v[36:39], v[168:171], v[192:195], v[36:39]
	v_mfma_f32_16x16x32_bf16 v[32:35], v[176:179], v[192:195], v[32:35]
	v_mfma_f32_16x16x32_bf16 v[20:23], v[168:171], v[208:211], v[20:23]
	v_mfma_f32_16x16x32_bf16 v[16:19], v[176:179], v[208:211], v[16:19]
	v_mfma_f32_16x16x32_bf16 v[4:7], v[168:171], v[216:219], v[4:7]
	v_mfma_f32_16x16x32_bf16 v[0:3], v[176:179], v[216:219], v[0:3]
	s_setprio 0
	s_barrier
	s_add_i32 s96, s96, 2
	s_add_u32 s56, s56, 0x100
	s_addc_u32 s95, s95, 0
	s_cmpk_gt_u32 s96, 0x7d
	s_mov_b64 s[48:49], s[54:55]
	s_cbranch_scc0 .LBB0_1146
	s_and_b64 vcc, exec, s[16:17]
	s_cbranch_vccz .LBB0_1149
	s_barrier
